# v8kperm
# speedup vs baseline: 1.0528x; 1.0036x over previous
; __device__ __forceinline__ void finishSM(f32x16& p0, f32x16& p1, float alpha, float& l_reg, bf16x8& pa0, bf16x8& pa1, bf16x8& pa2, bf16x8& pa3) {
; #pragma unroll
;     for (int r = 0; r < 16; ++r) p1[r] = __builtin_amdgcn_exp2f(p1[r]);
;     float ps = 0;
; #pragma unroll
;     for (int r = 0; r < 16; ++r) ps += p0[r];
; #pragma unroll
;     for (int r = 0; r < 16; ++r) ps += p1[r];
;     { auto rr = __builtin_amdgcn_permlane32_swap(__float_as_uint(ps), __float_as_uint(ps), false, false);
;       ps = __uint_as_float(rr[0]) + __uint_as_float(rr[1]); }
;     l_reg = l_reg * alpha + ps;
;     PK4(p0, 0, pa0); PK4(p0, 8, pa1); PK4(p1, 0, pa2); PK4(p1, 8, pa3);
; }
; __device__ __forceinline__ void pv_tile(f32x16* o, int vb0, bf16x8 pa0, bf16x8 pa1, bf16x8 pa2, bf16x8 pa3) {
;     ...
;     PV_D0(0); PV_D0(1); PV_D0(2); PV_D0(3);
;     ...
; }
.LBB0_323:
	v_add_f32_e32 v2, 0, v243
	v_add_f32_e32 v2, v242, v2
	v_add_f32_e32 v2, v241, v2
	v_add_f32_e32 v2, v240, v2
	v_add_f32_e32 v2, v239, v2
	v_add_f32_e32 v2, v238, v2
	v_add_f32_e32 v2, v237, v2
	v_add_f32_e32 v2, v236, v2
	v_add_f32_e32 v2, v235, v2
	v_add_f32_e32 v2, v234, v2
	v_add_f32_e32 v2, v233, v2
	v_add_f32_e32 v2, v232, v2
	v_exp_f32_e32 v10, v14
	v_add_f32_e32 v2, v231, v2
	v_exp_f32_e32 v11, v15
	v_add_f32_e32 v2, v230, v2
	v_exp_f32_e32 v12, v176
	v_add_f32_e32 v2, v216, v2
	v_exp_f32_e32 v13, v177
	v_add_f32_e32 v2, v179, v2
	v_exp_f32_e32 v14, v116
	v_add_f32_e32 v2, v10, v2
	v_exp_f32_e32 v15, v117
	v_add_f32_e32 v2, v11, v2
	v_exp_f32_e32 v80, v118
	v_add_f32_e32 v2, v12, v2
	v_exp_f32_e32 v81, v119
	v_add_f32_e32 v2, v13, v2
	v_exp_f32_e32 v82, v120
	v_add_f32_e32 v2, v14, v2
	v_exp_f32_e32 v83, v121
	v_add_f32_e32 v2, v15, v2
	v_exp_f32_e32 v84, v122
	v_add_f32_e32 v2, v80, v2
	v_exp_f32_e32 v85, v123
	v_add_f32_e32 v2, v81, v2
	v_exp_f32_e32 v86, v124
	v_add_f32_e32 v2, v82, v2
	v_exp_f32_e32 v87, v125
	v_add_f32_e32 v2, v83, v2
	v_exp_f32_e32 v88, v126
	v_add_f32_e32 v2, v84, v2
	v_exp_f32_e32 v89, v127
	v_add_f32_e32 v2, v85, v2
	v_add_f32_e32 v2, v86, v2
	v_add_f32_e32 v2, v87, v2
	v_add_f32_e32 v2, v88, v2
	v_add_f32_e32 v2, v89, v2
	v_mov_b32_e32 v3, v2
	s_nop 1
	v_permlane32_swap_b32_e32 v2, v3
	v_add_f32_e32 v2, v2, v3
	s_add_i32 s0, 0, 0xc000
	v_add_f32_e32 v0, v0, v2
	v_cvt_pk_bf16_f32 v2, v243, v242
	v_cvt_pk_bf16_f32 v3, v241, v240
	v_cvt_pk_bf16_f32 v4, v239, v238
	v_cvt_pk_bf16_f32 v5, v237, v236
	v_cvt_pk_bf16_f32 v6, v235, v234
	v_cvt_pk_bf16_f32 v7, v233, v232
	v_cvt_pk_bf16_f32 v8, v231, v230
	v_cvt_pk_bf16_f32 v9, v216, v179
	v_cvt_pk_bf16_f32 v10, v10, v11
	v_cvt_pk_bf16_f32 v11, v12, v13
	v_cvt_pk_bf16_f32 v12, v14, v15
	v_cvt_pk_bf16_f32 v13, v80, v81
	v_cvt_pk_bf16_f32 v80, v82, v83
	v_cvt_pk_bf16_f32 v81, v84, v85
	v_cvt_pk_bf16_f32 v82, v86, v87
	v_cvt_pk_bf16_f32 v83, v88, v89
	v_add_u32_e32 v14, s0, v218
	ds_read_b64_tr_b16 v[84:85], v14 offset:0
	ds_read_b64_tr_b16 v[86:87], v14 offset:0x800
	ds_read_b64_tr_b16 v[88:89], v14 offset:0x1000
	ds_read_b64_tr_b16 v[90:91], v14 offset:0x1800
	ds_read_b64_tr_b16 v[92:93], v14 offset:0x2000
	ds_read_b64_tr_b16 v[94:95], v14 offset:0x2800
	ds_read_b64_tr_b16 v[96:97], v14 offset:0x3000
	ds_read_b64_tr_b16 v[98:99], v14 offset:0x3800
	s_waitcnt lgkmcnt(0)
	v_mfma_f32_32x32x16_bf16 v[64:79], v[84:87], v[2:5], v[64:79]
	ds_read_b64_tr_b16 v[84:85], v14 offset:0x200
	ds_read_b64_tr_b16 v[86:87], v14 offset:0xa00
	v_mfma_f32_32x32x16_bf16 v[64:79], v[88:91], v[6:9], v[64:79]
	ds_read_b64_tr_b16 v[88:89], v14 offset:0x1200
	ds_read_b64_tr_b16 v[90:91], v14 offset:0x1a00
	s_mov_b32 s49, s81
	v_ashrrev_i32_e32 v181, 31, v180
	s_xor_b64 s[82:83], s[96:97], -1
	v_mfma_f32_32x32x16_bf16 v[64:79], v[92:95], v[10:13], v[64:79]
	ds_read_b64_tr_b16 v[92:93], v14 offset:0x2200
	ds_read_b64_tr_b16 v[94:95], v14 offset:0x2a00
	s_mov_b64 s[96:97], 0
	v_mfma_f32_32x32x16_bf16 v[64:79], v[96:99], v[80:83], v[64:79]
	ds_read_b64_tr_b16 v[96:97], v14 offset:0x3200
	ds_read_b64_tr_b16 v[98:99], v14 offset:0x3a00
	s_nop 0
	s_waitcnt lgkmcnt(0)
	s_nop 0
	v_mfma_f32_32x32x16_bf16 v[48:63], v[84:87], v[2:5], v[48:63]
	ds_read_b64_tr_b16 v[84:85], v14 offset:0x400
	ds_read_b64_tr_b16 v[86:87], v14 offset:0xc00
	v_mfma_f32_32x32x16_bf16 v[48:63], v[88:91], v[6:9], v[48:63]
	ds_read_b64_tr_b16 v[88:89], v14 offset:0x1400
	ds_read_b64_tr_b16 v[90:91], v14 offset:0x1c00
	v_mfma_f32_32x32x16_bf16 v[48:63], v[92:95], v[10:13], v[48:63]
	ds_read_b64_tr_b16 v[92:93], v14 offset:0x2400
	ds_read_b64_tr_b16 v[94:95], v14 offset:0x2c00
	v_mfma_f32_32x32x16_bf16 v[48:63], v[96:99], v[80:83], v[48:63]
	ds_read_b64_tr_b16 v[96:97], v14 offset:0x3400
	ds_read_b64_tr_b16 v[98:99], v14 offset:0x3c00
	s_nop 0
	s_waitcnt lgkmcnt(0)
	s_nop 0
	v_mfma_f32_32x32x16_bf16 v[32:47], v[84:87], v[2:5], v[32:47]
	ds_read_b64_tr_b16 v[84:85], v14 offset:0x600
	ds_read_b64_tr_b16 v[86:87], v14 offset:0xe00
	v_mfma_f32_32x32x16_bf16 v[32:47], v[88:91], v[6:9], v[32:47]
	ds_read_b64_tr_b16 v[88:89], v14 offset:0x1600
	ds_read_b64_tr_b16 v[90:91], v14 offset:0x1e00
	v_mfma_f32_32x32x16_bf16 v[32:47], v[92:95], v[10:13], v[32:47]
	ds_read_b64_tr_b16 v[92:93], v14 offset:0x2600
	ds_read_b64_tr_b16 v[94:95], v14 offset:0x2e00
	v_mfma_f32_32x32x16_bf16 v[32:47], v[96:99], v[80:83], v[32:47]
	ds_read_b64_tr_b16 v[96:97], v14 offset:0x3600
	ds_read_b64_tr_b16 v[98:99], v14 offset:0x3e00
	s_nop 0
	s_waitcnt lgkmcnt(0)
	s_barrier
; __device__ __forceinline__ float bf_lo(unsigned w) { return __uint_as_float(w << 16); }
; __device__ __forceinline__ float bf_hi(unsigned w) { return __uint_as_float(w & 0xffff0000u); }
; __device__ __forceinline__ float siluf_(float v) { return v * sigmoidf_(v); }
; __device__ __forceinline__ void attn_block(const Params& p, LAS unsigned char* lds, int h, int qb) {
;     ...
;     const float il = __builtin_amdgcn_rcpf(l_reg);
;     const bf16_t* zp = proj + (size_t)qrow * NP + C_ZA + h * 128; unsigned char* ya8 = p.ws + O_YA8;
; #pragma unroll
;     for (int d0 = 0; d0 < 4; ++d0)
; #pragma unroll
;         for (int rq = 0; rq < 4; ++rq) { const int dv = d0 * 32 + 8 * rq + 4 * hi; const u32x2 zz = *(const u32x2*)(zp + dv);
;             const float y0 = o[d0][rq * 4 + 0] * il * siluf_(bf_lo(zz.x)), y1 = o[d0][rq * 4 + 1] * il * siluf_(bf_hi(zz.x));
;             const float y2 = o[d0][rq * 4 + 2] * il * siluf_(bf_lo(zz.y)), y3 = o[d0][rq * 4 + 3] * il * siluf_(bf_hi(zz.y));
;             int x8 = __builtin_amdgcn_cvt_pk_fp8_f32(y0 * 64.f, y1 * 64.f, 0, false); x8 = __builtin_amdgcn_cvt_pk_fp8_f32(y2 * 64.f, y3 * 64.f, x8, true);
;             *(int*)(ya8 + (size_t)qrow * 1024 + h * 128 + dv) = x8; }
	v_mfma_f32_32x32x16_bf16 v[16:31], v[84:87], v[2:5], v[16:31]
	v_mov_b64_e32 v[2:3], s[14:15]
	v_mad_i64_i32 v[2:3], s[0:1], v180, s31, v[2:3]
	v_lshl_add_u64 v[2:3], v[2:3], 0, s[48:49]
	s_mov_b64 s[0:1], 0xe200880
	v_lshlrev_b64 v[4:5], 10, v[180:181]
	v_lshl_add_u64 v[4:5], s[64:65], 0, v[4:5]
	v_mfma_f32_32x32x16_bf16 v[16:31], v[88:91], v[6:9], v[16:31]
	v_lshlrev_b32_e32 v6, 3, v193
	v_mov_b32_e32 v7, v1
	v_lshl_add_u64 v[6:7], v[2:3], 0, v[6:7]
	v_lshl_add_u64 v[2:3], v[6:7], 0, s[0:1]
	global_load_dwordx2 v[128:129], v[2:3], off offset:0
	global_load_dwordx2 v[130:131], v[2:3], off offset:16
	global_load_dwordx2 v[132:133], v[2:3], off offset:32
	global_load_dwordx2 v[134:135], v[2:3], off offset:48
	global_load_dwordx2 v[136:137], v[2:3], off offset:64
	global_load_dwordx2 v[138:139], v[2:3], off offset:80
	global_load_dwordx2 v[140:141], v[2:3], off offset:96
	global_load_dwordx2 v[142:143], v[2:3], off offset:112
	global_load_dwordx2 v[144:145], v[2:3], off offset:128
	global_load_dwordx2 v[146:147], v[2:3], off offset:144
	global_load_dwordx2 v[148:149], v[2:3], off offset:160
	global_load_dwordx2 v[150:151], v[2:3], off offset:176
	global_load_dwordx2 v[152:153], v[2:3], off offset:192
	global_load_dwordx2 v[154:155], v[2:3], off offset:208
	global_load_dwordx2 v[156:157], v[2:3], off offset:224
	global_load_dwordx2 v[158:159], v[2:3], off offset:240
	s_mov_b32 s0, 0xe200000
	v_add_co_u32_e32 v6, vcc, s0, v6
	v_mfma_f32_32x32x16_bf16 v[16:31], v[92:95], v[10:13], v[16:31]
	s_nop 0
	v_addc_co_u32_e32 v7, vcc, 0, v7, vcc
	v_rcp_f32_e32 v8, v0
	v_lshlrev_b32_e32 v0, 2, v193
	v_lshl_add_u64 v[4:5], v[4:5], 0, v[0:1]
	s_and_b64 vcc, exec, s[82:83]
	v_mul_f32_e32 v9, v8, v64
	v_mul_f32_e32 v0, v8, v68
	v_mfma_f32_32x32x16_bf16 v[16:31], v[96:99], v[80:83], v[16:31]
	s_waitcnt vmcnt(15)
	v_mov_b32_e32 v6, v128
	v_mov_b32_e32 v7, v129
	v_lshlrev_b32_e32 v10, 16, v6
	v_mul_f32_e32 v11, 0xbfb8aa3b, v10
	v_exp_f32_e32 v11, v11
	v_and_b32_e32 v6, 0xffff0000, v6
	v_add_f32_e32 v11, 1.0, v11
	v_rcp_f32_e32 v11, v11
	s_nop 0
	v_mul_f32_e32 v10, v11, v10
	v_mul_f32_e32 v11, 0xbfb8aa3b, v6
	v_exp_f32_e32 v11, v11
	v_mul_f32_e32 v9, v9, v10
	v_mul_f32_e32 v10, v8, v65
	v_mul_f32_e32 v9, 0x42800000, v9
	v_add_f32_e32 v11, 1.0, v11
	v_rcp_f32_e32 v11, v11
	s_nop 0
	v_mul_f32_e32 v6, v11, v6
	v_lshlrev_b32_e32 v11, 16, v7
	v_mul_f32_e32 v12, 0xbfb8aa3b, v11
	v_exp_f32_e32 v12, v12
	v_and_b32_e32 v7, 0xffff0000, v7
	v_mul_f32_e32 v6, v10, v6
	v_mul_f32_e32 v10, v8, v66
	v_add_f32_e32 v12, 1.0, v12
	v_rcp_f32_e32 v12, v12
	v_mul_f32_e32 v6, 0x42800000, v6
	v_mul_f32_e32 v11, v12, v11
	v_mul_f32_e32 v12, 0xbfb8aa3b, v7
	v_exp_f32_e32 v12, v12
	v_mul_f32_e32 v10, v10, v11
	v_mul_f32_e32 v11, v8, v67
	v_add_f32_e32 v12, 1.0, v12
	v_rcp_f32_e32 v12, v12
	s_nop 0
	v_mul_f32_e32 v7, v12, v7
	v_mul_f32_e32 v7, v11, v7
	v_mov_b32_e32 v11, v1
	v_cvt_pk_fp8_f32 v11, v9, v6
	v_mul_f32_e32 v6, 0x42800000, v10
	v_mul_f32_e32 v7, 0x42800000, v7
	v_cvt_pk_fp8_f32 v11, v6, v7 op_sel:[0,0,1]
	global_store_dword v[4:5], v11, off
	s_waitcnt vmcnt(15)
	v_mov_b32_e32 v6, v130
	v_mov_b32_e32 v7, v131
	v_lshlrev_b32_e32 v9, 16, v6
	v_mul_f32_e32 v10, 0xbfb8aa3b, v9
	v_exp_f32_e32 v10, v10
	v_and_b32_e32 v6, 0xffff0000, v6
	v_add_f32_e32 v10, 1.0, v10
	v_rcp_f32_e32 v10, v10
	s_nop 0
	v_mul_f32_e32 v9, v10, v9
	v_mul_f32_e32 v10, 0xbfb8aa3b, v6
	v_exp_f32_e32 v10, v10
	v_mul_f32_e32 v0, v0, v9
	v_mul_f32_e32 v9, v8, v69
	v_mul_f32_e32 v0, 0x42800000, v0
	v_add_f32_e32 v10, 1.0, v10
	v_rcp_f32_e32 v10, v10
	s_nop 0
	v_mul_f32_e32 v6, v10, v6
	v_lshlrev_b32_e32 v10, 16, v7
	v_mul_f32_e32 v11, 0xbfb8aa3b, v10
	v_exp_f32_e32 v11, v11
	v_and_b32_e32 v7, 0xffff0000, v7
	v_mul_f32_e32 v6, v9, v6
	v_mul_f32_e32 v9, v8, v70
	v_add_f32_e32 v11, 1.0, v11
	v_rcp_f32_e32 v11, v11
	v_mul_f32_e32 v6, 0x42800000, v6
	v_mul_f32_e32 v10, v11, v10
	v_mul_f32_e32 v11, 0xbfb8aa3b, v7
	v_exp_f32_e32 v11, v11
	v_mul_f32_e32 v9, v9, v10
	v_mul_f32_e32 v10, v8, v71
	v_add_f32_e32 v11, 1.0, v11
	v_rcp_f32_e32 v11, v11
	s_nop 0
	v_mul_f32_e32 v7, v11, v7
	v_mul_f32_e32 v7, v10, v7
	v_mov_b32_e32 v10, v1
	v_cvt_pk_fp8_f32 v10, v0, v6
	v_mul_f32_e32 v0, 0x42800000, v9
	v_mul_f32_e32 v6, 0x42800000, v7
	v_cvt_pk_fp8_f32 v10, v0, v6 op_sel:[0,0,1]
	v_mul_f32_e32 v0, v8, v72
	global_store_dword v[4:5], v10, off offset:8
	s_waitcnt vmcnt(15)
	v_mov_b32_e32 v6, v132
	v_mov_b32_e32 v7, v133
	v_lshlrev_b32_e32 v9, 16, v6
	v_mul_f32_e32 v10, 0xbfb8aa3b, v9
	v_exp_f32_e32 v10, v10
	v_and_b32_e32 v6, 0xffff0000, v6
	v_add_f32_e32 v10, 1.0, v10
	v_rcp_f32_e32 v10, v10
	s_nop 0
	v_mul_f32_e32 v9, v10, v9
	v_mul_f32_e32 v10, 0xbfb8aa3b, v6
	v_exp_f32_e32 v10, v10
	v_mul_f32_e32 v0, v0, v9
	v_mul_f32_e32 v9, v8, v73
	v_mul_f32_e32 v0, 0x42800000, v0
	v_add_f32_e32 v10, 1.0, v10
	v_rcp_f32_e32 v10, v10
	s_nop 0
	v_mul_f32_e32 v6, v10, v6
	v_lshlrev_b32_e32 v10, 16, v7
	v_mul_f32_e32 v11, 0xbfb8aa3b, v10
	v_exp_f32_e32 v11, v11
	v_and_b32_e32 v7, 0xffff0000, v7
	v_mul_f32_e32 v6, v9, v6
	v_mul_f32_e32 v9, v8, v74
	v_add_f32_e32 v11, 1.0, v11
	v_rcp_f32_e32 v11, v11
	v_mul_f32_e32 v6, 0x42800000, v6
	v_mul_f32_e32 v10, v11, v10
	v_mul_f32_e32 v11, 0xbfb8aa3b, v7
	v_exp_f32_e32 v11, v11
	v_mul_f32_e32 v9, v9, v10
	v_mul_f32_e32 v10, v8, v75
	v_add_f32_e32 v11, 1.0, v11
	v_rcp_f32_e32 v11, v11
	s_nop 0
	v_mul_f32_e32 v7, v11, v7
	v_mul_f32_e32 v7, v10, v7
	v_mov_b32_e32 v10, v1
	v_cvt_pk_fp8_f32 v10, v0, v6
	v_mul_f32_e32 v0, 0x42800000, v9
	v_mul_f32_e32 v6, 0x42800000, v7
	v_cvt_pk_fp8_f32 v10, v0, v6 op_sel:[0,0,1]
	v_mul_f32_e32 v0, v8, v76
	global_store_dword v[4:5], v10, off offset:16
	s_waitcnt vmcnt(15)
; __device__ __forceinline__ float bf_lo(unsigned w) { return __uint_as_float(w << 16); }
; __device__ __forceinline__ float bf_hi(unsigned w) { return __uint_as_float(w & 0xffff0000u); }
; __device__ __forceinline__ float siluf_(float v) { return v * sigmoidf_(v); }
; __device__ __forceinline__ void attn_block(const Params& p, LAS unsigned char* lds, int h, int qb) {
;     ...
;     const float il = __builtin_amdgcn_rcpf(l_reg);
;     const bf16_t* zp = proj + (size_t)qrow * NP + C_ZA + h * 128; unsigned char* ya8 = p.ws + O_YA8;
; #pragma unroll
;     for (int d0 = 0; d0 < 4; ++d0)
; #pragma unroll
;         for (int rq = 0; rq < 4; ++rq) { const int dv = d0 * 32 + 8 * rq + 4 * hi; const u32x2 zz = *(const u32x2*)(zp + dv);
;             const float y0 = o[d0][rq * 4 + 0] * il * siluf_(bf_lo(zz.x)), y1 = o[d0][rq * 4 + 1] * il * siluf_(bf_hi(zz.x));
;             const float y2 = o[d0][rq * 4 + 2] * il * siluf_(bf_lo(zz.y)), y3 = o[d0][rq * 4 + 3] * il * siluf_(bf_hi(zz.y));
;             int x8 = __builtin_amdgcn_cvt_pk_fp8_f32(y0 * 64.f, y1 * 64.f, 0, false); x8 = __builtin_amdgcn_cvt_pk_fp8_f32(y2 * 64.f, y3 * 64.f, x8, true);
;             *(int*)(ya8 + (size_t)qrow * 1024 + h * 128 + dv) = x8; }
	v_mov_b32_e32 v6, v134
	v_mov_b32_e32 v7, v135
	v_lshlrev_b32_e32 v9, 16, v6
	v_mul_f32_e32 v10, 0xbfb8aa3b, v9
	v_exp_f32_e32 v10, v10
	v_and_b32_e32 v6, 0xffff0000, v6
	v_add_f32_e32 v10, 1.0, v10
	v_rcp_f32_e32 v10, v10
	s_nop 0
	v_mul_f32_e32 v9, v10, v9
	v_mul_f32_e32 v10, 0xbfb8aa3b, v6
	v_exp_f32_e32 v10, v10
	v_mul_f32_e32 v0, v0, v9
	v_mul_f32_e32 v9, v8, v77
	v_mul_f32_e32 v0, 0x42800000, v0
	v_add_f32_e32 v10, 1.0, v10
	v_rcp_f32_e32 v10, v10
	s_nop 0
	v_mul_f32_e32 v6, v10, v6
	v_lshlrev_b32_e32 v10, 16, v7
	v_mul_f32_e32 v11, 0xbfb8aa3b, v10
	v_exp_f32_e32 v11, v11
	v_and_b32_e32 v7, 0xffff0000, v7
	v_mul_f32_e32 v6, v9, v6
	v_mul_f32_e32 v9, v8, v78
	v_add_f32_e32 v11, 1.0, v11
	v_rcp_f32_e32 v11, v11
	v_mul_f32_e32 v6, 0x42800000, v6
	v_mul_f32_e32 v10, v11, v10
	v_mul_f32_e32 v11, 0xbfb8aa3b, v7
	v_exp_f32_e32 v11, v11
	v_mul_f32_e32 v9, v9, v10
	v_mul_f32_e32 v10, v8, v79
	v_add_f32_e32 v11, 1.0, v11
	v_rcp_f32_e32 v11, v11
	s_nop 0
	v_mul_f32_e32 v7, v11, v7
	v_mul_f32_e32 v7, v10, v7
	v_mov_b32_e32 v10, v1
	v_cvt_pk_fp8_f32 v10, v0, v6
	v_mul_f32_e32 v0, 0x42800000, v9
	v_mul_f32_e32 v6, 0x42800000, v7
	v_cvt_pk_fp8_f32 v10, v0, v6 op_sel:[0,0,1]
	v_mul_f32_e32 v0, v8, v48
	global_store_dword v[4:5], v10, off offset:24
	s_waitcnt vmcnt(15)
	v_mov_b32_e32 v6, v136
	v_mov_b32_e32 v7, v137
	v_lshlrev_b32_e32 v9, 16, v6
	v_mul_f32_e32 v10, 0xbfb8aa3b, v9
	v_exp_f32_e32 v10, v10
	v_and_b32_e32 v6, 0xffff0000, v6
	v_add_f32_e32 v10, 1.0, v10
	v_rcp_f32_e32 v10, v10
	s_nop 0
	v_mul_f32_e32 v9, v10, v9
	v_mul_f32_e32 v10, 0xbfb8aa3b, v6
	v_exp_f32_e32 v10, v10
	v_mul_f32_e32 v0, v0, v9
	v_mul_f32_e32 v9, v8, v49
	v_mul_f32_e32 v0, 0x42800000, v0
	v_add_f32_e32 v10, 1.0, v10
	v_rcp_f32_e32 v10, v10
	s_nop 0
	v_mul_f32_e32 v6, v10, v6
	v_lshlrev_b32_e32 v10, 16, v7
	v_mul_f32_e32 v11, 0xbfb8aa3b, v10
	v_exp_f32_e32 v11, v11
	v_and_b32_e32 v7, 0xffff0000, v7
	v_mul_f32_e32 v6, v9, v6
	v_mul_f32_e32 v9, v8, v50
	v_add_f32_e32 v11, 1.0, v11
	v_rcp_f32_e32 v11, v11
	v_mul_f32_e32 v6, 0x42800000, v6
	v_mul_f32_e32 v10, v11, v10
	v_mul_f32_e32 v11, 0xbfb8aa3b, v7
	v_exp_f32_e32 v11, v11
	v_mul_f32_e32 v9, v9, v10
	v_mul_f32_e32 v10, v8, v51
	v_add_f32_e32 v11, 1.0, v11
	v_rcp_f32_e32 v11, v11
	s_nop 0
	v_mul_f32_e32 v7, v11, v7
	v_mul_f32_e32 v7, v10, v7
	v_mov_b32_e32 v10, v1
	v_cvt_pk_fp8_f32 v10, v0, v6
	v_mul_f32_e32 v0, 0x42800000, v9
	v_mul_f32_e32 v6, 0x42800000, v7
	v_cvt_pk_fp8_f32 v10, v0, v6 op_sel:[0,0,1]
	v_mul_f32_e32 v0, v8, v52
	global_store_dword v[4:5], v10, off offset:32
	s_waitcnt vmcnt(15)
	v_mov_b32_e32 v6, v138
	v_mov_b32_e32 v7, v139
	v_lshlrev_b32_e32 v9, 16, v6
	v_mul_f32_e32 v10, 0xbfb8aa3b, v9
	v_exp_f32_e32 v10, v10
	v_and_b32_e32 v6, 0xffff0000, v6
	v_add_f32_e32 v10, 1.0, v10
	v_rcp_f32_e32 v10, v10
	s_nop 0
	v_mul_f32_e32 v9, v10, v9
	v_mul_f32_e32 v10, 0xbfb8aa3b, v6
	v_exp_f32_e32 v10, v10
	v_mul_f32_e32 v0, v0, v9
	v_mul_f32_e32 v9, v8, v53
	v_mul_f32_e32 v0, 0x42800000, v0
	v_add_f32_e32 v10, 1.0, v10
	v_rcp_f32_e32 v10, v10
	s_nop 0
	v_mul_f32_e32 v6, v10, v6
	v_lshlrev_b32_e32 v10, 16, v7
	v_mul_f32_e32 v11, 0xbfb8aa3b, v10
	v_exp_f32_e32 v11, v11
	v_and_b32_e32 v7, 0xffff0000, v7
	v_mul_f32_e32 v6, v9, v6
	v_mul_f32_e32 v9, v8, v54
	v_add_f32_e32 v11, 1.0, v11
	v_rcp_f32_e32 v11, v11
	v_mul_f32_e32 v6, 0x42800000, v6
	v_mul_f32_e32 v10, v11, v10
	v_mul_f32_e32 v11, 0xbfb8aa3b, v7
	v_exp_f32_e32 v11, v11
	v_mul_f32_e32 v9, v9, v10
	v_mul_f32_e32 v10, v8, v55
	v_add_f32_e32 v11, 1.0, v11
	v_rcp_f32_e32 v11, v11
	s_nop 0
	v_mul_f32_e32 v7, v11, v7
	v_mul_f32_e32 v7, v10, v7
	v_mov_b32_e32 v10, v1
	v_cvt_pk_fp8_f32 v10, v0, v6
	v_mul_f32_e32 v0, 0x42800000, v9
	v_mul_f32_e32 v6, 0x42800000, v7
	v_cvt_pk_fp8_f32 v10, v0, v6 op_sel:[0,0,1]
	v_mul_f32_e32 v0, v8, v56
	global_store_dword v[4:5], v10, off offset:40
	s_waitcnt vmcnt(15)
	v_mov_b32_e32 v6, v140
	v_mov_b32_e32 v7, v141
	v_lshlrev_b32_e32 v9, 16, v6
	v_mul_f32_e32 v10, 0xbfb8aa3b, v9
	v_exp_f32_e32 v10, v10
	v_and_b32_e32 v6, 0xffff0000, v6
	v_add_f32_e32 v10, 1.0, v10
	v_rcp_f32_e32 v10, v10
	s_nop 0
	v_mul_f32_e32 v9, v10, v9
	v_mul_f32_e32 v10, 0xbfb8aa3b, v6
	v_exp_f32_e32 v10, v10
	v_mul_f32_e32 v0, v0, v9
	v_mul_f32_e32 v9, v8, v57
	v_mul_f32_e32 v0, 0x42800000, v0
	v_add_f32_e32 v10, 1.0, v10
	v_rcp_f32_e32 v10, v10
	s_nop 0
	v_mul_f32_e32 v6, v10, v6
	v_lshlrev_b32_e32 v10, 16, v7
	v_mul_f32_e32 v11, 0xbfb8aa3b, v10
	v_exp_f32_e32 v11, v11
	v_and_b32_e32 v7, 0xffff0000, v7
	v_mul_f32_e32 v6, v9, v6
	v_mul_f32_e32 v9, v8, v58
	v_add_f32_e32 v11, 1.0, v11
	v_rcp_f32_e32 v11, v11
	v_mul_f32_e32 v6, 0x42800000, v6
	v_mul_f32_e32 v10, v11, v10
	v_mul_f32_e32 v11, 0xbfb8aa3b, v7
	v_exp_f32_e32 v11, v11
	v_mul_f32_e32 v9, v9, v10
	v_mul_f32_e32 v10, v8, v59
	v_add_f32_e32 v11, 1.0, v11
	v_rcp_f32_e32 v11, v11
	s_nop 0
	v_mul_f32_e32 v7, v11, v7
	v_mul_f32_e32 v7, v10, v7
	v_mov_b32_e32 v10, v1
	v_cvt_pk_fp8_f32 v10, v0, v6
	v_mul_f32_e32 v0, 0x42800000, v9
	v_mul_f32_e32 v6, 0x42800000, v7
	v_cvt_pk_fp8_f32 v10, v0, v6 op_sel:[0,0,1]
	v_mul_f32_e32 v0, v8, v60
	global_store_dword v[4:5], v10, off offset:48
	s_waitcnt vmcnt(15)
; __device__ __forceinline__ float bf_lo(unsigned w) { return __uint_as_float(w << 16); }
; __device__ __forceinline__ float bf_hi(unsigned w) { return __uint_as_float(w & 0xffff0000u); }
; __device__ __forceinline__ float siluf_(float v) { return v * sigmoidf_(v); }
; __device__ __forceinline__ void attn_block(const Params& p, LAS unsigned char* lds, int h, int qb) {
;     ...
;     const float il = __builtin_amdgcn_rcpf(l_reg);
;     const bf16_t* zp = proj + (size_t)qrow * NP + C_ZA + h * 128; unsigned char* ya8 = p.ws + O_YA8;
; #pragma unroll
;     for (int d0 = 0; d0 < 4; ++d0)
; #pragma unroll
;         for (int rq = 0; rq < 4; ++rq) { const int dv = d0 * 32 + 8 * rq + 4 * hi; const u32x2 zz = *(const u32x2*)(zp + dv);
;             const float y0 = o[d0][rq * 4 + 0] * il * siluf_(bf_lo(zz.x)), y1 = o[d0][rq * 4 + 1] * il * siluf_(bf_hi(zz.x));
;             const float y2 = o[d0][rq * 4 + 2] * il * siluf_(bf_lo(zz.y)), y3 = o[d0][rq * 4 + 3] * il * siluf_(bf_hi(zz.y));
;             int x8 = __builtin_amdgcn_cvt_pk_fp8_f32(y0 * 64.f, y1 * 64.f, 0, false); x8 = __builtin_amdgcn_cvt_pk_fp8_f32(y2 * 64.f, y3 * 64.f, x8, true);
;             *(int*)(ya8 + (size_t)qrow * 1024 + h * 128 + dv) = x8; }
	v_mov_b32_e32 v6, v142
	v_mov_b32_e32 v7, v143
	v_lshlrev_b32_e32 v9, 16, v6
	v_mul_f32_e32 v10, 0xbfb8aa3b, v9
	v_exp_f32_e32 v10, v10
	v_and_b32_e32 v6, 0xffff0000, v6
	v_add_f32_e32 v10, 1.0, v10
	v_rcp_f32_e32 v10, v10
	s_nop 0
	v_mul_f32_e32 v9, v10, v9
	v_mul_f32_e32 v10, 0xbfb8aa3b, v6
	v_exp_f32_e32 v10, v10
	v_mul_f32_e32 v0, v0, v9
	v_mul_f32_e32 v9, v8, v61
	v_mul_f32_e32 v0, 0x42800000, v0
	v_add_f32_e32 v10, 1.0, v10
	v_rcp_f32_e32 v10, v10
	s_nop 0
	v_mul_f32_e32 v6, v10, v6
	v_lshlrev_b32_e32 v10, 16, v7
	v_mul_f32_e32 v11, 0xbfb8aa3b, v10
	v_exp_f32_e32 v11, v11
	v_and_b32_e32 v7, 0xffff0000, v7
	v_mul_f32_e32 v6, v9, v6
	v_mul_f32_e32 v9, v8, v62
	v_add_f32_e32 v11, 1.0, v11
	v_rcp_f32_e32 v11, v11
	v_mul_f32_e32 v6, 0x42800000, v6
	v_mul_f32_e32 v10, v11, v10
	v_mul_f32_e32 v11, 0xbfb8aa3b, v7
	v_exp_f32_e32 v11, v11
	v_mul_f32_e32 v9, v9, v10
	v_mul_f32_e32 v10, v8, v63
	v_add_f32_e32 v11, 1.0, v11
	v_rcp_f32_e32 v11, v11
	s_nop 0
	v_mul_f32_e32 v7, v11, v7
	v_mul_f32_e32 v7, v10, v7
	v_mov_b32_e32 v10, v1
	v_cvt_pk_fp8_f32 v10, v0, v6
	v_mul_f32_e32 v0, 0x42800000, v9
	v_mul_f32_e32 v6, 0x42800000, v7
	v_cvt_pk_fp8_f32 v10, v0, v6 op_sel:[0,0,1]
	v_mul_f32_e32 v0, v8, v32
	global_store_dword v[4:5], v10, off offset:56
	s_waitcnt vmcnt(15)
	v_mov_b32_e32 v6, v144
	v_mov_b32_e32 v7, v145
	v_lshlrev_b32_e32 v9, 16, v6
	v_mul_f32_e32 v10, 0xbfb8aa3b, v9
	v_exp_f32_e32 v10, v10
	v_and_b32_e32 v6, 0xffff0000, v6
	v_add_f32_e32 v10, 1.0, v10
	v_rcp_f32_e32 v10, v10
	s_nop 0
	v_mul_f32_e32 v9, v10, v9
	v_mul_f32_e32 v10, 0xbfb8aa3b, v6
	v_exp_f32_e32 v10, v10
	v_mul_f32_e32 v0, v0, v9
	v_mul_f32_e32 v9, v8, v33
	v_mul_f32_e32 v0, 0x42800000, v0
	v_add_f32_e32 v10, 1.0, v10
	v_rcp_f32_e32 v10, v10
	s_nop 0
	v_mul_f32_e32 v6, v10, v6
	v_lshlrev_b32_e32 v10, 16, v7
	v_mul_f32_e32 v11, 0xbfb8aa3b, v10
	v_exp_f32_e32 v11, v11
	v_and_b32_e32 v7, 0xffff0000, v7
	v_mul_f32_e32 v6, v9, v6
	v_mul_f32_e32 v9, v8, v34
	v_add_f32_e32 v11, 1.0, v11
	v_rcp_f32_e32 v11, v11
	v_mul_f32_e32 v6, 0x42800000, v6
	v_mul_f32_e32 v10, v11, v10
	v_mul_f32_e32 v11, 0xbfb8aa3b, v7
	v_exp_f32_e32 v11, v11
	v_mul_f32_e32 v9, v9, v10
	v_mul_f32_e32 v10, v8, v35
	v_add_f32_e32 v11, 1.0, v11
	v_rcp_f32_e32 v11, v11
	s_nop 0
	v_mul_f32_e32 v7, v11, v7
	v_mul_f32_e32 v7, v10, v7
	v_mov_b32_e32 v10, v1
	v_cvt_pk_fp8_f32 v10, v0, v6
	v_mul_f32_e32 v0, 0x42800000, v9
	v_mul_f32_e32 v6, 0x42800000, v7
	v_cvt_pk_fp8_f32 v10, v0, v6 op_sel:[0,0,1]
	v_mul_f32_e32 v0, v8, v36
	global_store_dword v[4:5], v10, off offset:64
	s_waitcnt vmcnt(15)
	v_mov_b32_e32 v6, v146
	v_mov_b32_e32 v7, v147
	v_lshlrev_b32_e32 v9, 16, v6
	v_mul_f32_e32 v10, 0xbfb8aa3b, v9
	v_exp_f32_e32 v10, v10
	v_and_b32_e32 v6, 0xffff0000, v6
	v_add_f32_e32 v10, 1.0, v10
	v_rcp_f32_e32 v10, v10
	s_nop 0
	v_mul_f32_e32 v9, v10, v9
	v_mul_f32_e32 v10, 0xbfb8aa3b, v6
	v_exp_f32_e32 v10, v10
	v_mul_f32_e32 v0, v0, v9
	v_mul_f32_e32 v9, v8, v37
	v_mul_f32_e32 v0, 0x42800000, v0
	v_add_f32_e32 v10, 1.0, v10
	v_rcp_f32_e32 v10, v10
	s_nop 0
	v_mul_f32_e32 v6, v10, v6
	v_lshlrev_b32_e32 v10, 16, v7
	v_mul_f32_e32 v11, 0xbfb8aa3b, v10
	v_exp_f32_e32 v11, v11
	v_and_b32_e32 v7, 0xffff0000, v7
	v_mul_f32_e32 v6, v9, v6
	v_mul_f32_e32 v9, v8, v38
	v_add_f32_e32 v11, 1.0, v11
	v_rcp_f32_e32 v11, v11
	v_mul_f32_e32 v6, 0x42800000, v6
	v_mul_f32_e32 v10, v11, v10
	v_mul_f32_e32 v11, 0xbfb8aa3b, v7
	v_exp_f32_e32 v11, v11
	v_mul_f32_e32 v9, v9, v10
	v_mul_f32_e32 v10, v8, v39
	v_add_f32_e32 v11, 1.0, v11
	v_rcp_f32_e32 v11, v11
	s_nop 0
	v_mul_f32_e32 v7, v11, v7
	v_mul_f32_e32 v7, v10, v7
	v_mov_b32_e32 v10, v1
	v_cvt_pk_fp8_f32 v10, v0, v6
	v_mul_f32_e32 v0, 0x42800000, v9
	v_mul_f32_e32 v6, 0x42800000, v7
	v_cvt_pk_fp8_f32 v10, v0, v6 op_sel:[0,0,1]
	v_mul_f32_e32 v0, v8, v40
	global_store_dword v[4:5], v10, off offset:72
	s_waitcnt vmcnt(15)
	v_mov_b32_e32 v6, v148
	v_mov_b32_e32 v7, v149
	v_lshlrev_b32_e32 v9, 16, v6
	v_mul_f32_e32 v10, 0xbfb8aa3b, v9
	v_exp_f32_e32 v10, v10
	v_and_b32_e32 v6, 0xffff0000, v6
	v_add_f32_e32 v10, 1.0, v10
	v_rcp_f32_e32 v10, v10
	s_nop 0
	v_mul_f32_e32 v9, v10, v9
	v_mul_f32_e32 v10, 0xbfb8aa3b, v6
	v_exp_f32_e32 v10, v10
	v_mul_f32_e32 v0, v0, v9
	v_mul_f32_e32 v9, v8, v41
	v_mul_f32_e32 v0, 0x42800000, v0
	v_add_f32_e32 v10, 1.0, v10
	v_rcp_f32_e32 v10, v10
	s_nop 0
	v_mul_f32_e32 v6, v10, v6
	v_lshlrev_b32_e32 v10, 16, v7
	v_mul_f32_e32 v11, 0xbfb8aa3b, v10
	v_exp_f32_e32 v11, v11
	v_and_b32_e32 v7, 0xffff0000, v7
	v_mul_f32_e32 v6, v9, v6
	v_mul_f32_e32 v9, v8, v42
	v_add_f32_e32 v11, 1.0, v11
	v_rcp_f32_e32 v11, v11
	v_mul_f32_e32 v6, 0x42800000, v6
	v_mul_f32_e32 v10, v11, v10
	v_mul_f32_e32 v11, 0xbfb8aa3b, v7
	v_exp_f32_e32 v11, v11
	v_mul_f32_e32 v9, v9, v10
	v_mul_f32_e32 v10, v8, v43
	v_add_f32_e32 v11, 1.0, v11
	v_rcp_f32_e32 v11, v11
	s_nop 0
	v_mul_f32_e32 v7, v11, v7
	v_mul_f32_e32 v7, v10, v7
	v_mov_b32_e32 v10, v1
	v_cvt_pk_fp8_f32 v10, v0, v6
	v_mul_f32_e32 v0, 0x42800000, v9
	v_mul_f32_e32 v6, 0x42800000, v7
	v_cvt_pk_fp8_f32 v10, v0, v6 op_sel:[0,0,1]
	v_mul_f32_e32 v0, v8, v44
	global_store_dword v[4:5], v10, off offset:80
	s_waitcnt vmcnt(15)
; __device__ __forceinline__ float bf_lo(unsigned w) { return __uint_as_float(w << 16); }
; __device__ __forceinline__ float bf_hi(unsigned w) { return __uint_as_float(w & 0xffff0000u); }
; __device__ __forceinline__ float siluf_(float v) { return v * sigmoidf_(v); }
; __device__ __forceinline__ void attn_block(const Params& p, LAS unsigned char* lds, int h, int qb) {
;     ...
;     const float il = __builtin_amdgcn_rcpf(l_reg);
;     const bf16_t* zp = proj + (size_t)qrow * NP + C_ZA + h * 128; unsigned char* ya8 = p.ws + O_YA8;
; #pragma unroll
;     for (int d0 = 0; d0 < 4; ++d0)
; #pragma unroll
;         for (int rq = 0; rq < 4; ++rq) { const int dv = d0 * 32 + 8 * rq + 4 * hi; const u32x2 zz = *(const u32x2*)(zp + dv);
;             const float y0 = o[d0][rq * 4 + 0] * il * siluf_(bf_lo(zz.x)), y1 = o[d0][rq * 4 + 1] * il * siluf_(bf_hi(zz.x));
;             const float y2 = o[d0][rq * 4 + 2] * il * siluf_(bf_lo(zz.y)), y3 = o[d0][rq * 4 + 3] * il * siluf_(bf_hi(zz.y));
;             int x8 = __builtin_amdgcn_cvt_pk_fp8_f32(y0 * 64.f, y1 * 64.f, 0, false); x8 = __builtin_amdgcn_cvt_pk_fp8_f32(y2 * 64.f, y3 * 64.f, x8, true);
;             *(int*)(ya8 + (size_t)qrow * 1024 + h * 128 + dv) = x8; }
	v_mov_b32_e32 v6, v150
	v_mov_b32_e32 v7, v151
	v_lshlrev_b32_e32 v9, 16, v6
	v_mul_f32_e32 v10, 0xbfb8aa3b, v9
	v_exp_f32_e32 v10, v10
	v_and_b32_e32 v6, 0xffff0000, v6
	v_add_f32_e32 v10, 1.0, v10
	v_rcp_f32_e32 v10, v10
	s_nop 0
	v_mul_f32_e32 v9, v10, v9
	v_mul_f32_e32 v10, 0xbfb8aa3b, v6
	v_exp_f32_e32 v10, v10
	v_mul_f32_e32 v0, v0, v9
	v_mul_f32_e32 v9, v8, v45
	v_mul_f32_e32 v0, 0x42800000, v0
	v_add_f32_e32 v10, 1.0, v10
	v_rcp_f32_e32 v10, v10
	s_nop 0
	v_mul_f32_e32 v6, v10, v6
	v_lshlrev_b32_e32 v10, 16, v7
	v_mul_f32_e32 v11, 0xbfb8aa3b, v10
	v_exp_f32_e32 v11, v11
	v_and_b32_e32 v7, 0xffff0000, v7
	v_mul_f32_e32 v6, v9, v6
	v_mul_f32_e32 v9, v8, v46
	v_add_f32_e32 v11, 1.0, v11
	v_rcp_f32_e32 v11, v11
	v_mul_f32_e32 v6, 0x42800000, v6
	v_mul_f32_e32 v10, v11, v10
	v_mul_f32_e32 v11, 0xbfb8aa3b, v7
	v_exp_f32_e32 v11, v11
	v_mul_f32_e32 v9, v9, v10
	v_mul_f32_e32 v10, v8, v47
	v_add_f32_e32 v11, 1.0, v11
	v_rcp_f32_e32 v11, v11
	s_nop 0
	v_mul_f32_e32 v7, v11, v7
	v_mul_f32_e32 v7, v10, v7
	v_mov_b32_e32 v10, v1
	v_cvt_pk_fp8_f32 v10, v0, v6
	v_mul_f32_e32 v0, 0x42800000, v9
	v_mul_f32_e32 v6, 0x42800000, v7
	v_cvt_pk_fp8_f32 v10, v0, v6 op_sel:[0,0,1]
	v_mul_f32_e32 v0, v8, v16
	global_store_dword v[4:5], v10, off offset:88
	s_waitcnt vmcnt(15)
	v_mov_b32_e32 v6, v152
	v_mov_b32_e32 v7, v153
	v_lshlrev_b32_e32 v9, 16, v6
	v_mul_f32_e32 v10, 0xbfb8aa3b, v9
	v_exp_f32_e32 v10, v10
	v_and_b32_e32 v6, 0xffff0000, v6
	v_add_f32_e32 v10, 1.0, v10
	v_rcp_f32_e32 v10, v10
	s_nop 0
	v_mul_f32_e32 v9, v10, v9
	v_mul_f32_e32 v10, 0xbfb8aa3b, v6
	v_exp_f32_e32 v10, v10
	v_mul_f32_e32 v0, v0, v9
	v_mul_f32_e32 v9, v8, v17
	v_mul_f32_e32 v0, 0x42800000, v0
	v_add_f32_e32 v10, 1.0, v10
	v_rcp_f32_e32 v10, v10
	s_nop 0
	v_mul_f32_e32 v6, v10, v6
	v_lshlrev_b32_e32 v10, 16, v7
	v_mul_f32_e32 v11, 0xbfb8aa3b, v10
	v_exp_f32_e32 v11, v11
	v_and_b32_e32 v7, 0xffff0000, v7
	v_mul_f32_e32 v6, v9, v6
	v_mul_f32_e32 v9, v8, v18
	v_add_f32_e32 v11, 1.0, v11
	v_rcp_f32_e32 v11, v11
	v_mul_f32_e32 v6, 0x42800000, v6
	v_mul_f32_e32 v10, v11, v10
	v_mul_f32_e32 v11, 0xbfb8aa3b, v7
	v_exp_f32_e32 v11, v11
	v_mul_f32_e32 v9, v9, v10
	v_mul_f32_e32 v10, v8, v19
	v_add_f32_e32 v11, 1.0, v11
	v_rcp_f32_e32 v11, v11
	s_nop 0
	v_mul_f32_e32 v7, v11, v7
	v_mul_f32_e32 v7, v10, v7
	v_mov_b32_e32 v10, v1
	v_cvt_pk_fp8_f32 v10, v0, v6
	v_mul_f32_e32 v0, 0x42800000, v9
	v_mul_f32_e32 v6, 0x42800000, v7
	v_cvt_pk_fp8_f32 v10, v0, v6 op_sel:[0,0,1]
	v_mul_f32_e32 v0, v8, v20
	global_store_dword v[4:5], v10, off offset:96
	s_waitcnt vmcnt(15)
	v_mov_b32_e32 v6, v154
	v_mov_b32_e32 v7, v155
	v_lshlrev_b32_e32 v9, 16, v6
	v_mul_f32_e32 v10, 0xbfb8aa3b, v9
	v_exp_f32_e32 v10, v10
	v_and_b32_e32 v6, 0xffff0000, v6
	v_add_f32_e32 v10, 1.0, v10
	v_rcp_f32_e32 v10, v10
	s_nop 0
	v_mul_f32_e32 v9, v10, v9
	v_mul_f32_e32 v10, 0xbfb8aa3b, v6
	v_exp_f32_e32 v10, v10
	v_mul_f32_e32 v0, v0, v9
	v_mul_f32_e32 v9, v8, v21
	v_mul_f32_e32 v0, 0x42800000, v0
	v_add_f32_e32 v10, 1.0, v10
	v_rcp_f32_e32 v10, v10
	s_nop 0
	v_mul_f32_e32 v6, v10, v6
	v_lshlrev_b32_e32 v10, 16, v7
	v_mul_f32_e32 v11, 0xbfb8aa3b, v10
	v_exp_f32_e32 v11, v11
	v_and_b32_e32 v7, 0xffff0000, v7
	v_mul_f32_e32 v6, v9, v6
	v_mul_f32_e32 v9, v8, v22
	v_add_f32_e32 v11, 1.0, v11
	v_rcp_f32_e32 v11, v11
	v_mul_f32_e32 v6, 0x42800000, v6
	v_mul_f32_e32 v10, v11, v10
	v_mul_f32_e32 v11, 0xbfb8aa3b, v7
	v_exp_f32_e32 v11, v11
	v_mul_f32_e32 v9, v9, v10
	v_mul_f32_e32 v10, v8, v23
	v_add_f32_e32 v11, 1.0, v11
	v_rcp_f32_e32 v11, v11
	s_nop 0
	v_mul_f32_e32 v7, v11, v7
	v_mul_f32_e32 v7, v10, v7
	v_mov_b32_e32 v10, v1
	v_cvt_pk_fp8_f32 v10, v0, v6
	v_mul_f32_e32 v0, 0x42800000, v9
	v_mul_f32_e32 v6, 0x42800000, v7
	v_cvt_pk_fp8_f32 v10, v0, v6 op_sel:[0,0,1]
	v_mul_f32_e32 v0, v8, v24
	global_store_dword v[4:5], v10, off offset:104
	s_waitcnt vmcnt(15)
	v_mov_b32_e32 v6, v156
	v_mov_b32_e32 v7, v157
	v_lshlrev_b32_e32 v9, 16, v6
	v_mul_f32_e32 v10, 0xbfb8aa3b, v9
	v_exp_f32_e32 v10, v10
	v_and_b32_e32 v6, 0xffff0000, v6
	v_add_f32_e32 v10, 1.0, v10
	v_rcp_f32_e32 v10, v10
	s_nop 0
	v_mul_f32_e32 v9, v10, v9
	v_mul_f32_e32 v10, 0xbfb8aa3b, v6
	v_exp_f32_e32 v10, v10
	v_mul_f32_e32 v0, v0, v9
	v_mul_f32_e32 v9, v8, v25
	v_mul_f32_e32 v0, 0x42800000, v0
	v_add_f32_e32 v10, 1.0, v10
	v_rcp_f32_e32 v10, v10
	s_nop 0
	v_mul_f32_e32 v6, v10, v6
	v_lshlrev_b32_e32 v10, 16, v7
	v_mul_f32_e32 v11, 0xbfb8aa3b, v10
	v_exp_f32_e32 v11, v11
	v_and_b32_e32 v7, 0xffff0000, v7
	v_mul_f32_e32 v6, v9, v6
	v_mul_f32_e32 v9, v8, v26
	v_add_f32_e32 v11, 1.0, v11
	v_rcp_f32_e32 v11, v11
	v_mul_f32_e32 v6, 0x42800000, v6
	v_mul_f32_e32 v10, v11, v10
	v_mul_f32_e32 v11, 0xbfb8aa3b, v7
	v_exp_f32_e32 v11, v11
	v_mul_f32_e32 v9, v9, v10
	v_mul_f32_e32 v10, v8, v27
	v_add_f32_e32 v11, 1.0, v11
	v_rcp_f32_e32 v11, v11
	s_nop 0
	v_mul_f32_e32 v7, v11, v7
	v_mul_f32_e32 v7, v10, v7
	v_mov_b32_e32 v10, v1
	v_cvt_pk_fp8_f32 v10, v0, v6
	v_mul_f32_e32 v0, 0x42800000, v9
	v_mul_f32_e32 v6, 0x42800000, v7
	v_cvt_pk_fp8_f32 v10, v0, v6 op_sel:[0,0,1]
	v_mul_f32_e32 v0, v8, v28
	global_store_dword v[4:5], v10, off offset:112
	s_waitcnt vmcnt(15)
	v_mov_b32_e32 v2, v158
	v_mov_b32_e32 v3, v159
	v_lshlrev_b32_e32 v6, 16, v2
	v_mul_f32_e32 v7, 0xbfb8aa3b, v6
	v_exp_f32_e32 v7, v7
	v_and_b32_e32 v2, 0xffff0000, v2
	v_add_f32_e32 v7, 1.0, v7
	v_rcp_f32_e32 v7, v7
	s_nop 0
	v_mul_f32_e32 v6, v7, v6
	v_mul_f32_e32 v7, 0xbfb8aa3b, v2
	v_exp_f32_e32 v7, v7
	v_mul_f32_e32 v0, v0, v6
	v_mul_f32_e32 v6, v8, v29
	v_mul_f32_e32 v0, 0x42800000, v0
	v_add_f32_e32 v7, 1.0, v7
	v_rcp_f32_e32 v7, v7
	s_nop 0
	v_mul_f32_e32 v2, v7, v2
	v_lshlrev_b32_e32 v7, 16, v3
	v_mul_f32_e32 v9, 0xbfb8aa3b, v7
	v_exp_f32_e32 v9, v9
	v_mul_f32_e32 v2, v6, v2
	v_mul_f32_e32 v6, v8, v30
	v_and_b32_e32 v3, 0xffff0000, v3
	v_add_f32_e32 v9, 1.0, v9
	v_rcp_f32_e32 v9, v9
	v_mul_f32_e32 v2, 0x42800000, v2
	v_mul_f32_e32 v7, v9, v7
	v_mul_f32_e32 v6, v6, v7
	v_mul_f32_e32 v7, v8, v31
	v_mul_f32_e32 v8, 0xbfb8aa3b, v3
	v_exp_f32_e32 v8, v8
	s_nop 0
	v_add_f32_e32 v8, 1.0, v8
	v_rcp_f32_e32 v8, v8
	s_nop 0
	v_mul_f32_e32 v3, v8, v3
	v_mul_f32_e32 v3, v7, v3
	v_mov_b32_e32 v7, v1
	v_cvt_pk_fp8_f32 v7, v0, v2
	v_mul_f32_e32 v0, 0x42800000, v6
	v_mul_f32_e32 v2, 0x42800000, v3
	v_cvt_pk_fp8_f32 v7, v0, v2 op_sel:[0,0,1]
	global_store_dword v[4:5], v7, off offset:120
	s_cbranch_vccnz .LBB0_320
; #define LAS __attribute__((address_space(3)))
; __device__ __forceinline__ int otid() { int t = threadIdx.x; asm volatile("" : "+v"(t)); return t; }
; __device__ __forceinline__ unsigned lds_addr(LAS unsigned char* p) { return (unsigned)(size_t)p; }
; __device__ __forceinline__ void qkt(int kboff, f32x16& p0, f32x16& p1, LAS unsigned char* lds, int r32, int hi, const bf16x8* qr) {
;     p0 = (f32x16){}; p1 = (f32x16){};
;     unsigned kb[4];
; #pragma unroll
;     for (int dd = 0; dd < 4; ++dd) kb[dd] = lds_addr(lds) + K_OFF + kboff + r32 * 384 + (((2 * dd + hi) ^ ((r32 >> 1) & 7)) << 4);
; __device__ __forceinline__ void attn_block(const Params& p, LAS unsigned char* lds, int h, int qb) {
;     const int tid = otid(), wid = __builtin_amdgcn_readfirstlane(tid >> 6), lane = tid & 63, r32 = lane & 31, hi = lane >> 5;
;     const bf16_t* qbuf = (const bf16_t*)(p.ws + O_Q); const bf16_t* Kh = (const bf16_t*)(p.ws + O_K) + h * 192; const bf16_t* Vh = (const bf16_t*)(p.ws + O_V) + h * 128;
;     bf16_t* proj = (bf16_t*)(p.ws + O_PROJ);
;     const int qrow = qb * 256 + wid * 32 + r32;
;     bf16x8 qr[12];
;     { const bf16_t* qp = qbuf + (size_t)qrow * QW + h * 192 + hi * 8;
; #pragma unroll
;       for (int d0 = 0; d0 < 12; ++d0) qr[d0] = *(const bf16x8*)(qp + d0 * 16); }
;     const int ntiles = qb * 4 + 4, my_last = qb * 4 + (wid >> 1);
;     int ksrc[3], vsrc[2];
; #pragma unroll
;     for (int i = 0; i < 3; ++i) { const int j = i * 512 + tid, row = j / 24, cp = j % 24, c = (cp & ~7) | ((cp & 7) ^ ((row >> 1) & 7)); ksrc[i] = (row * KW + c * 8) * 2; }
; #pragma unroll
;     for (int i = 0; i < 2; ++i) { const int off = (i * 512 + tid) * 16, sub = off >> 9, rem = (off & 511) >> 1, kk = (sub >> 2) * 8 + (rem >> 5), c = (sub & 3) * 32 + (rem & 31);
;         const int k = (kk & ~0xC) | ((kk & 4) << 1) | ((kk & 8) >> 1); vsrc[i] = (k * VW + c) * 2; }
;     const int vb0 = (int)lds_addr(lds) + v_rd_base(lane);
;     const unsigned ldsw = (unsigned)wid * 1024u;
;     ...
;     float m_reg = -1e30f, l_reg = 0.f; f32x16 o[4];
; #pragma unroll
;     for (int j = 0; j < 4; ++j) o[j] = (f32x16){};
;     f32x16 pA0, pA1, pB0, pB1; float mnA, mnB, alA = 1.f, alB = 1.f; bf16x8 pa0, pa1, pa2, pa3;
;     ...
;     ADMA(0, 0, 0); __syncthreads();
;     ADMA(1, 1, 1);
.LBB0_324:
	v_mov_b32_e32 v8, v199
	s_and_b64 s[0:1], s[96:97], exec
	s_cselect_b32 s34, s16, s53
	v_readfirstlane_b32 s35, v8
	s_ashr_i32 s17, s35, 6
	s_lshl_b32 s0, s34, 8
	s_lshl_b32 s1, s17, 5
	v_and_b32_e32 v47, 31, v8
	s_add_i32 s1, s1, s0
	v_bfe_u32 v193, v8, 5, 1
	v_or_b32_e32 v180, s1, v47
	v_mov_b64_e32 v[2:3], s[44:45]
	v_mad_i64_i32 v[2:3], s[0:1], v180, s60, v[2:3]
	v_lshlrev_b32_e32 v0, 4, v193
	v_lshl_add_u64 v[2:3], v[2:3], 0, v[0:1]
	global_load_dwordx4 v[128:131], v[2:3], off
	global_load_dwordx4 v[132:135], v[2:3], off offset:32
	global_load_dwordx4 v[136:139], v[2:3], off offset:64
	global_load_dwordx4 v[140:143], v[2:3], off offset:96
	global_load_dwordx4 v[144:147], v[2:3], off offset:128
	global_load_dwordx4 v[148:151], v[2:3], off offset:160
	global_load_dwordx4 v[152:155], v[2:3], off offset:192
	global_load_dwordx4 v[156:159], v[2:3], off offset:224
	global_load_dwordx4 v[160:163], v[2:3], off offset:256
	global_load_dwordx4 v[164:167], v[2:3], off offset:288
	global_load_dwordx4 v[168:171], v[2:3], off offset:320
	global_load_dwordx4 v[172:175], v[2:3], off offset:352
	s_mov_b32 s0, 0x2aaaaaab
	v_mul_hi_i32 v0, v8, s0
	v_lshrrev_b32_e32 v2, 31, v0
	v_ashrrev_i32_e32 v0, 2, v0
	v_add_u32_e32 v0, v0, v2
	v_mul_lo_u32 v2, v0, 24
	v_sub_u32_e32 v2, v8, v2
	v_lshrrev_b32_e32 v3, 1, v0
	v_bitop3_b32 v2, v3, v2, 7 bitop3:0x6c
	v_mul_lo_u32 v0, v0, s60
	v_lshl_add_u32 v34, v2, 4, v0
	v_add_u32_e32 v0, 0x200, v8
	v_mul_hi_i32 v2, v0, s0
	v_lshrrev_b32_e32 v3, 31, v2
	v_ashrrev_i32_e32 v2, 2, v2
	v_add_u32_e32 v2, v2, v3
	v_mul_lo_u32 v3, v2, 24
	v_sub_u32_e32 v0, v0, v3
	v_lshrrev_b32_e32 v3, 1, v2
	v_bitop3_b32 v0, v3, v0, 7 bitop3:0x6c
	v_mul_lo_u32 v2, v2, s60
	v_lshl_add_u32 v36, v0, 4, v2
	v_add_u32_e32 v0, 0x400, v8
	v_mul_hi_i32 v2, v0, s0
	v_lshrrev_b32_e32 v3, 31, v2
	v_ashrrev_i32_e32 v2, 2, v2
	v_add_u32_e32 v2, v2, v3
	v_mul_lo_u32 v3, v2, 24
	v_sub_u32_e32 v0, v0, v3
	v_lshrrev_b32_e32 v3, 1, v2
	v_bitop3_b32 v0, v3, v0, 7 bitop3:0x6c
	v_lshlrev_b32_e32 v3, 4, v8
	v_mul_lo_u32 v2, v2, s60
	v_add_u32_e32 v10, 0x2000, v3
	v_lshl_add_u32 v38, v0, 4, v2
	v_lshrrev_b32_e32 v9, 1, v8
	v_bfe_i32 v2, v8, 4, 24
	v_ashrrev_i32_e32 v10, 8, v10
	v_and_b32_e32 v5, 63, v8
	v_bfe_u32 v0, v8, 2, 2
	v_and_b32_e32 v40, 8, v9
	v_lshlrev_b32_e32 v6, 1, v8
	v_and_b32_e32 v44, 0x1ffff0, v2
	v_lshrrev_b32_e32 v2, 1, v2
	v_and_b32_e32 v43, 0x1ffff0, v10
	v_lshrrev_b32_e32 v10, 1, v10
	v_or_b32_e32 v4, v40, v0
	v_and_b32_e32 v41, 0xc0, v6
	v_and_b32_e32 v42, 48, v3
	v_and_b32_e32 v46, 4, v2
	v_and_b32_e32 v45, 4, v10
	v_lshlrev_b32_e32 v5, 3, v5
	v_and_b32_e32 v3, 0xc0, v3
	s_lshl_b32 s0, s17, 10
	s_add_i32 s80, 0, 0x10000
	v_or_b32_e32 v7, v42, v41
	v_or3_b32 v2, v44, v46, v4
	v_or3_b32 v4, v43, v45, v4
	v_and_or_b32 v3, v5, 24, v3
	v_and_b32_e32 v6, 32, v6
	v_and_b32_e32 v5, 0x100, v5
	s_add_i32 s1, s80, s0
	v_ashrrev_i32_e32 v35, 31, v34
	v_lshl_or_b32 v2, v2, 11, v7
	v_lshl_or_b32 v4, v4, 11, v7
	v_or3_b32 v218, v3, v6, v5
	v_lshl_add_u64 v[6:7], s[42:43], 0, v[34:35]
	s_mov_b32 m0, s1
	v_ashrrev_i32_e32 v37, 31, v36
	global_load_lds_dwordx4 v[6:7], off
	v_lshl_add_u64 v[6:7], s[42:43], 0, v[36:37]
	s_add_i32 m0, s1, 0x2000
	v_ashrrev_i32_e32 v39, 31, v38
	global_load_lds_dwordx4 v[6:7], off
	v_lshl_add_u64 v[6:7], s[42:43], 0, v[38:39]
	s_add_i32 m0, s1, 0x4000
	s_add_i32 s17, s0, 0
	v_ashrrev_i32_e32 v3, 31, v2
	global_load_lds_dwordx4 v[6:7], off
	v_lshl_add_u64 v[6:7], s[12:13], 0, v[2:3]
	s_mov_b32 m0, s17
	v_ashrrev_i32_e32 v5, 31, v4
	global_load_lds_dwordx4 v[6:7], off
	v_lshl_add_u64 v[6:7], s[12:13], 0, v[4:5]
	s_add_i32 m0, s17, 0x2000
	s_add_i32 s49, s17, 0x16000
	global_load_lds_dwordx4 v[6:7], off
	v_lshl_add_u64 v[6:7], s[66:67], 0, v[34:35]
	s_mov_b32 m0, s49
	s_add_i32 s0, s17, 0x18000
	s_waitcnt vmcnt(0) lgkmcnt(0)
	s_barrier
	global_load_lds_dwordx4 v[6:7], off
	v_lshl_add_u64 v[6:7], s[66:67], 0, v[36:37]
	s_mov_b32 m0, s0
	s_add_i32 s1, s17, 0x1a000
	global_load_lds_dwordx4 v[6:7], off
	v_lshl_add_u64 v[6:7], s[66:67], 0, v[38:39]
	s_mov_b32 m0, s1
	v_lshl_add_u64 v[2:3], s[68:69], 0, v[2:3]
	global_load_lds_dwordx4 v[6:7], off
	s_add_i32 m0, s17, 0x4000
	s_nop 0
	global_load_lds_dwordx4 v[2:3], off
	v_lshl_add_u64 v[2:3], s[68:69], 0, v[4:5]
	s_add_i32 m0, s17, 0x6000
	v_bitop3_b32 v4, v193, v9, 7 bitop3:0x78
	global_load_lds_dwordx4 v[2:3], off
	v_bfe_u32 v3, v8, 1, 3
	v_lshlrev_b32_e32 v48, 4, v4
	v_bitop3_b32 v4, v193, v3, 2 bitop3:0x36
	v_mov_b32_e32 v2, s80
	s_movk_i32 s80, 0x180
	v_lshlrev_b32_e32 v49, 4, v4
	v_bitop3_b32 v4, v193, v3, 4 bitop3:0x36
	v_bitop3_b32 v3, v193, v3, 6 bitop3:0x36
	v_mad_u32_u24 v2, v47, s80, v2
	v_lshlrev_b32_e32 v50, 4, v4
	v_lshlrev_b32_e32 v51, 4, v3
	v_add_u32_e32 v181, v48, v2
	v_add_u32_e32 v219, v49, v2
	v_add_u32_e32 v220, v50, v2
	v_add_u32_e32 v221, v51, v2
	v_and_b32_e32 v52, 31, v199
	v_bfe_u32 v53, v199, 5, 1
	v_bfe_u32 v54, v52, 2, 1
	v_bfe_u32 v55, v52, 3, 1
	v_xor_b32_e32 v54, v54, v55
	v_mul_u32_u24_e32 v55, 12, v54
	v_xor_b32_e32 v56, v52, v55
	v_sub_u32_e32 v57, v56, v52
	v_mul_i32_i24_e32 v57, 0x180, v57
	v_bfe_u32 v54, v52, 1, 3
	v_bfe_u32 v55, v56, 1, 3
	v_or_b32_e32 v58, 0, v53
	v_xor_b32_e32 v59, v58, v55
	v_xor_b32_e32 v60, v58, v54
	v_sub_u32_e32 v59, v59, v60
	v_lshl_add_u32 v59, v59, 4, v57
	v_add_u32_e32 v181, v181, v59
	v_or_b32_e32 v58, 2, v53
	v_xor_b32_e32 v59, v58, v55
	v_xor_b32_e32 v60, v58, v54
	v_sub_u32_e32 v59, v59, v60
	v_lshl_add_u32 v59, v59, 4, v57
	v_add_u32_e32 v219, v219, v59
	v_or_b32_e32 v58, 4, v53
	v_xor_b32_e32 v59, v58, v55
	v_xor_b32_e32 v60, v58, v54
	v_sub_u32_e32 v59, v59, v60
	v_lshl_add_u32 v59, v59, 4, v57
	v_add_u32_e32 v220, v220, v59
	v_or_b32_e32 v58, 6, v53
	v_xor_b32_e32 v59, v58, v55
	v_xor_b32_e32 v60, v58, v54
	v_sub_u32_e32 v59, v59, v60
	v_lshl_add_u32 v59, v59, 4, v57
	v_add_u32_e32 v221, v221, v59
	ds_read_b128 v[2:5], v181 offset:0
	ds_read_b128 v[6:9], v181 offset:0x3000
	ds_read_b128 v[52:55], v219 offset:0
	ds_read_b128 v[56:59], v219 offset:0x3000
	s_cmp_lt_i32 s34, 0
	s_waitcnt lgkmcnt(0)
; #define LAS __attribute__((address_space(3)))
; __device__ __forceinline__ unsigned lds_addr(LAS unsigned char* p) { return (unsigned)(size_t)p; }
; #define KGRP(B_, g_) do { KRD(B_[0], kb[(2 * (g_)) & 3], ((2 * (g_)) >> 2) * 128); KRD(B_[1], kb[(2 * (g_)) & 3], ((2 * (g_)) >> 2) * 128 + 12288); \
;                           KRD(B_[2], kb[(2 * (g_) + 1) & 3], ((2 * (g_) + 1) >> 2) * 128); KRD(B_[3], kb[(2 * (g_) + 1) & 3], ((2 * (g_) + 1) >> 2) * 128 + 12288); } while (0)
; #define KWAIT(B_, n_) asm volatile("s_waitcnt lgkmcnt(" #n_ ")" : "+v"(B_[0]), "+v"(B_[1]), "+v"(B_[2]), "+v"(B_[3]) :: "memory")
; #define KWAIT(B_, n_) asm volatile("s_waitcnt lgkmcnt(" #n_ ")" : "+v"(B_[0]), "+v"(B_[1]) :: "memory")
; __device__ __forceinline__ void partialSM(f32x16& p0, f32x16& p1, float& m_reg, float& mn, float& alpha) {
;     float pmax = p0[0];
; #pragma unroll
;     for (int r = 1; r < 16; ++r) pmax = fmaxf(pmax, p0[r]);
; #pragma unroll
;     for (int r = 0; r < 16; ++r) pmax = fmaxf(pmax, p1[r]);
;     { auto rr = __builtin_amdgcn_permlane32_swap(__float_as_uint(pmax), __float_as_uint(pmax), false, false);
;       pmax = fmaxf(__uint_as_float(rr[0]), __uint_as_float(rr[1])); }
;     constexpr float C2 = 1.4426950408889634f * SCALE;
;     if (__builtin_expect(__all((pmax - m_reg) * SCALE <= THR), 1)) { mn = m_reg; alpha = 1.f; }
;     else { mn = fmaxf(m_reg, pmax); alpha = __builtin_amdgcn_exp2f((m_reg - mn) * C2); m_reg = mn; }
;     const float mnL = -mn * C2;
; #pragma unroll
;     for (int r = 0; r < 16; ++r) p0[r] = fmaf(p0[r], C2, mnL);
; #pragma unroll
;     for (int r = 0; r < 16; ++r) p1[r] = fmaf(p1[r], C2, mnL);
; #pragma unroll
;     for (int r = 0; r < 16; ++r) p0[r] = __builtin_amdgcn_exp2f(p0[r]);
; }
; __device__ __forceinline__ void qkt(int kboff, f32x16& p0, f32x16& p1, LAS unsigned char* lds, int r32, int hi, const bf16x8* qr) {
;     p0 = (f32x16){}; p1 = (f32x16){};
;     unsigned kb[4];
; #pragma unroll
;     for (int dd = 0; dd < 4; ++dd) kb[dd] = lds_addr(lds) + K_OFF + kboff + r32 * 384 + (((2 * dd + hi) ^ ((r32 >> 1) & 7)) << 4);
;     ...
;     bf16x8 bA[4];
;     KGRP(bA, 0); KWAIT(bA, 0); KMMA(bA, 0);
;     KGRP(bA, 1); KWAIT(bA, 0); KMMA(bA, 1);
;     KGRP(bA, 2); KWAIT(bA, 0); KMMA(bA, 2);
;     KGRP(bA, 3); KWAIT(bA, 0); KMMA(bA, 3);
;     KGRP(bA, 4); KWAIT(bA, 0); KMMA(bA, 4);
;     KGRP(bA, 5); KWAIT(bA, 0); KMMA(bA, 5);
	s_nop 0
	v_mfma_f32_32x32x16_bf16 v[18:33], v[2:5], v[128:131], 0
	v_mfma_f32_32x32x16_bf16 v[2:17], v[6:9], v[128:131], 0
	v_mfma_f32_32x32x16_bf16 v[18:33], v[52:55], v[132:135], v[18:33]
	ds_read_b128 v[52:55], v220 offset:0
	v_mfma_f32_32x32x16_bf16 v[2:17], v[56:59], v[132:135], v[2:17]
	ds_read_b128 v[56:59], v220 offset:0x3000
	ds_read_b128 v[60:63], v221 offset:0
	ds_read_b128 v[64:67], v221 offset:0x3000
	s_nop 0
	s_waitcnt lgkmcnt(0)
	s_nop 0
	v_mfma_f32_32x32x16_bf16 v[18:33], v[52:55], v[136:139], v[18:33]
	ds_read_b128 v[52:55], v181 offset:0x80
	v_mfma_f32_32x32x16_bf16 v[2:17], v[56:59], v[136:139], v[2:17]
	ds_read_b128 v[56:59], v181 offset:0x3080
	v_mfma_f32_32x32x16_bf16 v[18:33], v[60:63], v[140:143], v[18:33]
	ds_read_b128 v[60:63], v219 offset:0x80
	v_mfma_f32_32x32x16_bf16 v[2:17], v[64:67], v[140:143], v[2:17]
	ds_read_b128 v[64:67], v219 offset:0x3080
	s_nop 0
	s_waitcnt lgkmcnt(0)
	s_nop 0
	v_mfma_f32_32x32x16_bf16 v[18:33], v[52:55], v[144:147], v[18:33]
	ds_read_b128 v[52:55], v220 offset:0x80
	v_mfma_f32_32x32x16_bf16 v[2:17], v[56:59], v[144:147], v[2:17]
	ds_read_b128 v[56:59], v220 offset:0x3080
	v_mfma_f32_32x32x16_bf16 v[18:33], v[60:63], v[148:151], v[18:33]
	ds_read_b128 v[60:63], v221 offset:0x80
	v_mfma_f32_32x32x16_bf16 v[2:17], v[64:67], v[148:151], v[2:17]
	ds_read_b128 v[64:67], v221 offset:0x3080
	s_nop 0
	s_waitcnt lgkmcnt(0)
	s_nop 0
	v_mfma_f32_32x32x16_bf16 v[18:33], v[52:55], v[152:155], v[18:33]
	ds_read_b128 v[52:55], v181 offset:0x100
	v_mfma_f32_32x32x16_bf16 v[2:17], v[56:59], v[152:155], v[2:17]
	ds_read_b128 v[56:59], v181 offset:0x3100
	v_mfma_f32_32x32x16_bf16 v[18:33], v[60:63], v[156:159], v[18:33]
	ds_read_b128 v[60:63], v219 offset:0x100
	v_mfma_f32_32x32x16_bf16 v[2:17], v[64:67], v[156:159], v[2:17]
	ds_read_b128 v[64:67], v219 offset:0x3100
	s_nop 0
	s_waitcnt lgkmcnt(0)
	s_nop 0
	v_mfma_f32_32x32x16_bf16 v[18:33], v[52:55], v[160:163], v[18:33]
	ds_read_b128 v[52:55], v220 offset:0x100
	v_mfma_f32_32x32x16_bf16 v[2:17], v[56:59], v[160:163], v[2:17]
	ds_read_b128 v[56:59], v220 offset:0x3100
	v_mfma_f32_32x32x16_bf16 v[18:33], v[60:63], v[164:167], v[18:33]
	ds_read_b128 v[60:63], v221 offset:0x100
	v_mfma_f32_32x32x16_bf16 v[2:17], v[64:67], v[164:167], v[2:17]
	ds_read_b128 v[64:67], v221 offset:0x3100
	s_nop 0
	s_waitcnt lgkmcnt(0)
	s_waitcnt vmcnt(0) lgkmcnt(0)
	s_barrier
	v_mfma_f32_32x32x16_bf16 v[18:33], v[52:55], v[168:171], v[18:33]
	v_mfma_f32_32x32x16_bf16 v[18:33], v[60:63], v[172:175], v[18:33]
	v_mfma_f32_32x32x16_bf16 v[2:17], v[56:59], v[168:171], v[2:17]
	s_nop 10
	v_max_f32_e32 v52, v19, v19
	v_max_f32_e32 v53, v18, v18
	v_max_f32_e32 v52, v53, v52
	v_max3_f32 v52, v52, v20, v21
	v_max3_f32 v52, v52, v22, v23
	v_max3_f32 v52, v52, v24, v25
	v_max3_f32 v52, v52, v26, v27
	v_mfma_f32_32x32x16_bf16 v[2:17], v[64:67], v[172:175], v[2:17]
	v_max3_f32 v52, v52, v28, v29
	v_max3_f32 v52, v52, v30, v31
	v_max3_f32 v52, v52, v32, v33
	s_nop 8
	v_max3_f32 v52, v52, v2, v3
	v_max3_f32 v52, v52, v4, v5
	v_max3_f32 v52, v52, v6, v7
	v_max3_f32 v52, v52, v8, v9
	v_max3_f32 v52, v52, v10, v11
	v_max3_f32 v52, v52, v12, v13
	v_max3_f32 v52, v52, v14, v15
	v_max3_f32 v52, v52, v16, v17
	v_mov_b32_e32 v53, v52
	s_nop 1
	v_permlane32_swap_b32_e32 v52, v53
	v_max_f32_e32 v53, v53, v53
	v_max_f32_e32 v52, v52, v52
	v_max_f32_e32 v52, v52, v53
	v_add_f32_e32 v53, 0x7149f2ca, v52
	v_mul_f32_e32 v53, 0x3d93cd3a, v53
	v_cmp_ge_f32_e32 vcc, s63, v53
	s_cbranch_scc1 .LBB0_339
	s_lshl_b32 s34, s34, 2
	s_ashr_i32 s84, s35, 7
	s_add_i32 s80, s34, 4
	s_add_i32 s84, s84, s34
	s_cmp_eq_u64 vcc, exec
	v_max_f32_e32 v52, v52, v52
	v_max_f32_e32 v53, 0xf149f2ca, v52
	s_cselect_b64 vcc, -1, 0
	v_mov_b32_e32 v52, 0xf149f2ca
	v_cndmask_b32_e32 v244, v53, v52, vcc
	v_mul_f32_e32 v52, 0xbdd53b94, v244
	v_pk_fma_f32 v[214:215], v[2:3], s[52:53], v[52:53] op_sel_hi:[1,0,0]
	v_sub_f32_e32 v2, 0xf149f2ca, v53
	v_mul_f32_e32 v2, 0x3dd53b94, v2
	v_exp_f32_e32 v2, v2
	v_fmamk_f32 v18, v18, 0x3dd53b94, v52
	v_exp_f32_e32 v80, v18
	v_fmamk_f32 v18, v19, 0x3dd53b94, v52
	v_exp_f32_e32 v81, v18
	v_fmamk_f32 v18, v20, 0x3dd53b94, v52
	v_exp_f32_e32 v82, v18
	v_fmamk_f32 v18, v21, 0x3dd53b94, v52
	v_cndmask_b32_e64 v192, v2, 1.0, vcc
	v_add_u32_e32 v2, v44, v40
	v_exp_f32_e32 v83, v18
	v_fmamk_f32 v18, v22, 0x3dd53b94, v52
	v_add3_u32 v2, v2, v46, v0
	v_mul_u32_u24_e32 v47, 0x180, v47
	v_exp_f32_e32 v84, v18
	v_fmamk_f32 v18, v23, 0x3dd53b94, v52
	s_add_i32 s34, 0, 0x16000
	v_lshl_or_b32 v2, v2, 11, v41
	v_exp_f32_e32 v85, v18
	v_fmamk_f32 v18, v24, 0x3dd53b94, v52
	v_add_u32_e32 v3, s34, v47
	v_add_u32_e32 v2, v2, v42
	v_exp_f32_e32 v86, v18
	v_fmamk_f32 v18, v25, 0x3dd53b94, v52
	v_add_u32_e32 v226, v48, v3
	v_add_u32_e32 v227, v49, v3
	v_add_u32_e32 v228, v50, v3
	v_add_u32_e32 v229, v51, v3
	v_ashrrev_i32_e32 v3, 31, v2
	v_exp_f32_e32 v87, v18
	v_fmamk_f32 v18, v26, 0x3dd53b94, v52
	v_lshl_add_u64 v[182:183], s[50:51], 0, v[2:3]
	v_add_u32_e32 v2, v43, v40
	v_exp_f32_e32 v88, v18
	v_fmamk_f32 v18, v27, 0x3dd53b94, v52
	v_add3_u32 v0, v2, v45, v0
	v_exp_f32_e32 v89, v18
	v_fmamk_f32 v18, v28, 0x3dd53b94, v52
	v_fmamk_f32 v19, v29, 0x3dd53b94, v52
	v_fmamk_f32 v20, v30, 0x3dd53b94, v52
	v_fmamk_f32 v21, v31, 0x3dd53b94, v52
	v_fmamk_f32 v22, v32, 0x3dd53b94, v52
	v_fmamk_f32 v23, v33, 0x3dd53b94, v52
	v_lshl_or_b32 v0, v0, 11, v41
	v_exp_f32_e32 v90, v18
	v_exp_f32_e32 v91, v19
	v_add_u32_e32 v2, v0, v42
	v_exp_f32_e32 v92, v20
	v_exp_f32_e32 v93, v21
	v_exp_f32_e32 v94, v22
	v_exp_f32_e32 v95, v23
	v_pk_fma_f32 v[202:203], v[14:15], s[52:53], v[52:53] op_sel_hi:[1,0,0]
	v_ashrrev_i32_e32 v3, 31, v2
; __device__ __forceinline__ unsigned lds_addr(LAS unsigned char* p) { return (unsigned)(size_t)p; }
; __device__ __forceinline__ int v_rd_base(int lane) { return ((lane & 3) << 3) | (((lane >> 2) & 3) << 6) | (((lane >> 4) & 1) << 5) | (((lane >> 5) & 1) << 8); }
; __device__ __forceinline__ void attn_block(const Params& p, LAS unsigned char* lds, int h, int qb) {
;     ...
;     int ksrc[3], vsrc[2];
; #pragma unroll
;     for (int i = 0; i < 3; ++i) { const int j = i * 512 + tid, row = j / 24, cp = j % 24, c = (cp & ~7) | ((cp & 7) ^ ((row >> 1) & 7)); ksrc[i] = (row * KW + c * 8) * 2; }
; #pragma unroll
;     for (int i = 0; i < 2; ++i) { const int off = (i * 512 + tid) * 16, sub = off >> 9, rem = (off & 511) >> 1, kk = (sub >> 2) * 8 + (rem >> 5), c = (sub & 3) * 32 + (rem & 31);
;         const int k = (kk & ~0xC) | ((kk & 4) << 1) | ((kk & 8) >> 1); vsrc[i] = (k * VW + c) * 2; }
;     const int vb0 = (int)lds_addr(lds) + v_rd_base(lane);
;     const unsigned ldsw = (unsigned)wid * 1024u;
;     ...
;     float m_reg = -1e30f, l_reg = 0.f; f32x16 o[4];
; #pragma unroll
;     for (int j = 0; j < 4; ++j) o[j] = (f32x16){};
	v_mov_b32_e32 v14, v1
	v_mov_b32_e32 v15, v1
	v_pk_fma_f32 v[200:201], v[16:17], s[52:53], v[52:53] op_sel_hi:[1,0,0]
	v_pk_fma_f32 v[204:205], v[12:13], s[52:53], v[52:53] op_sel_hi:[1,0,0]
	v_pk_fma_f32 v[206:207], v[10:11], s[52:53], v[52:53] op_sel_hi:[1,0,0]
	v_pk_fma_f32 v[208:209], v[8:9], s[52:53], v[52:53] op_sel_hi:[1,0,0]
	v_pk_fma_f32 v[210:211], v[6:7], s[52:53], v[52:53] op_sel_hi:[1,0,0]
	v_pk_fma_f32 v[212:213], v[4:5], s[52:53], v[52:53] op_sel_hi:[1,0,0]
	v_lshl_add_u64 v[184:185], s[50:51], 0, v[2:3]
	v_lshl_add_u64 v[186:187], s[40:41], 0, v[34:35]
	v_lshl_add_u64 v[188:189], s[40:41], 0, v[36:37]
	v_lshl_add_u64 v[190:191], s[40:41], 0, v[38:39]
	v_mov_b32_e32 v0, v1
	v_mov_b32_e32 v2, v1
	v_mov_b32_e32 v3, v1
	v_mov_b32_e32 v4, v1
	v_mov_b32_e32 v5, v1
	v_mov_b32_e32 v6, v1
	v_mov_b32_e32 v7, v1
	v_mov_b32_e32 v8, v1
	v_mov_b32_e32 v9, v1
	v_mov_b32_e32 v10, v1
	v_mov_b32_e32 v11, v1
	v_mov_b32_e32 v12, v1
	v_mov_b32_e32 v13, v1
	v_mov_b64_e32 v[30:31], v[14:15]
	v_mov_b64_e32 v[46:47], v[14:15]
	v_mov_b64_e32 v[62:63], v[14:15]
	v_mov_b64_e32 v[78:79], v[14:15]
	v_add_u32_e32 v225, 0, v218
	v_mov_b32_e32 v230, 0
	s_mov_b32 s86, 1
	s_mov_b32 s85, 0x10000
	v_mov_b64_e32 v[28:29], v[12:13]
	v_mov_b64_e32 v[26:27], v[10:11]
	v_mov_b64_e32 v[24:25], v[8:9]
	v_mov_b64_e32 v[22:23], v[6:7]
	v_mov_b64_e32 v[20:21], v[4:5]
	v_mov_b64_e32 v[18:19], v[2:3]
	v_mov_b64_e32 v[16:17], v[0:1]
	v_mov_b64_e32 v[44:45], v[12:13]
	v_mov_b64_e32 v[42:43], v[10:11]
	v_mov_b64_e32 v[40:41], v[8:9]
	v_mov_b64_e32 v[38:39], v[6:7]
	v_mov_b64_e32 v[36:37], v[4:5]
	v_mov_b64_e32 v[34:35], v[2:3]
	v_mov_b64_e32 v[32:33], v[0:1]
	v_mov_b64_e32 v[60:61], v[12:13]
	v_mov_b64_e32 v[58:59], v[10:11]
	v_mov_b64_e32 v[56:57], v[8:9]
	v_mov_b64_e32 v[54:55], v[6:7]
	v_mov_b64_e32 v[52:53], v[4:5]
	v_mov_b64_e32 v[50:51], v[2:3]
	v_mov_b64_e32 v[48:49], v[0:1]
	v_mov_b64_e32 v[76:77], v[12:13]
	v_mov_b64_e32 v[74:75], v[10:11]
	v_mov_b64_e32 v[72:73], v[8:9]
	v_mov_b64_e32 v[70:71], v[6:7]
	v_mov_b64_e32 v[68:69], v[4:5]
	v_mov_b64_e32 v[66:67], v[2:3]
	v_mov_b64_e32 v[64:65], v[0:1]
	s_mov_b64 s[54:55], 0x2ba60000
	s_mov_b64 s[56:57], 0x2ea40000
	v_mul_u32_u24_e32 v4, 0xaab, v199
	v_lshrrev_b32_e32 v4, 16, v4
	v_mul_u32_u24_e32 v5, 24, v4
	v_sub_u32_e32 v5, v199, v5
	v_bfe_u32 v6, v4, 1, 3
	v_and_b32_e32 v7, 7, v5
	v_xor_b32_e32 v7, v7, v6
	v_and_or_b32 v7, v5, 24, v7
	v_mul_u32_u24_e32 v4, 0xc00, v4
	v_lshl_add_u32 v8, v7, 4, v4
	v_lshl_add_u64 v[10:11], s[14:15], 0, v[186:187]
	v_lshl_add_u64 v[10:11], v[10:11], 0, s[54:55]
	v_sub_co_u32_e64 v10, s[98:99], v10, v8
	s_nop 1
	v_subbrev_co_u32_e64 v11, s[98:99], 0, v11, s[98:99]
	v_lshrrev_b32_e32 v4, 7, v199
	v_bfe_u32 v5, v199, 2, 3
	v_lshl_or_b32 v4, v4, 3, v5
	v_and_b32_e32 v5, 0xfffffff3, v4
	v_and_b32_e32 v6, 4, v4
	v_lshl_or_b32 v5, v6, 1, v5
	v_and_b32_e32 v6, 8, v4
	v_lshrrev_b32_e32 v6, 1, v6
	v_or_b32_e32 v5, v5, v6
	v_bfe_u32 v6, v199, 5, 2
	v_and_b32_e32 v7, 3, v199
	v_lshlrev_b32_e32 v6, 6, v6
	v_lshl_or_b32 v6, v7, 4, v6
	v_lshl_add_u32 v9, v5, 11, v6
	v_lshl_add_u64 v[12:13], s[14:15], 0, v[182:183]
	v_lshl_add_u64 v[12:13], v[12:13], 0, s[56:57]
	v_sub_co_u32_e64 v12, s[98:99], v12, v9
	s_nop 1
	v_subbrev_co_u32_e64 v13, s[98:99], 0, v13, s[98:99]
	s_nop 1
	v_readfirstlane_b32 s54, v10
	v_readfirstlane_b32 s55, v11
	v_readfirstlane_b32 s56, v12
	v_readfirstlane_b32 s57, v13
	v_mul_u32_u24_e32 v4, 0xaab, v199
	v_lshrrev_b32_e32 v4, 16, v4
	v_mul_u32_u24_e32 v5, 24, v4
	v_sub_u32_e32 v5, v199, v5
	v_bfe_u32 v6, v4, 1, 3
	v_and_b32_e32 v7, 7, v5
	v_xor_b32_e32 v7, v7, v6
	v_and_or_b32 v7, v5, 24, v7
	v_mul_u32_u24_e32 v4, 0xc00, v4
	v_lshl_add_u32 v186, v7, 4, v4
	v_add_u32_e32 v3, 256, v199
	v_mul_u32_u24_e32 v4, 0xaab, v3
	v_lshrrev_b32_e32 v4, 16, v4
	v_mul_u32_u24_e32 v5, 24, v4
	v_sub_u32_e32 v5, v3, v5
	v_bfe_u32 v6, v4, 1, 3
	v_and_b32_e32 v7, 7, v5
	v_xor_b32_e32 v7, v7, v6
	v_and_or_b32 v7, v5, 24, v7
	v_mul_u32_u24_e32 v4, 0xc00, v4
; __device__ __forceinline__ unsigned lds_addr(LAS unsigned char* p) { return (unsigned)(size_t)p; }
; __device__ __forceinline__ int v_rd_base(int lane) { return ((lane & 3) << 3) | (((lane >> 2) & 3) << 6) | (((lane >> 4) & 1) << 5) | (((lane >> 5) & 1) << 8); }
; __device__ __forceinline__ void stage_qk_fin(int kboff, f32x16& x0, f32x16& x1, LAS unsigned char* lds, int r32, int hi, const bf16x8* qr,
;                                              f32x16& y0, f32x16& y1, float alY, float& l_reg, bf16x8& pa0, bf16x8& pa1, bf16x8& pa2, bf16x8& pa3) {
;     ...
;     unsigned kb[4];
; #pragma unroll
;     for (int dd = 0; dd < 4; ++dd) kb[dd] = lds_addr(lds) + K_OFF + kboff + r32 * 384 + (((2 * dd + hi) ^ ((r32 >> 1) & 7)) << 4);
; __device__ __forceinline__ void attn_block(const Params& p, LAS unsigned char* lds, int h, int qb) {
;     ...
;     int ksrc[3], vsrc[2];
; #pragma unroll
;     for (int i = 0; i < 3; ++i) { const int j = i * 512 + tid, row = j / 24, cp = j % 24, c = (cp & ~7) | ((cp & 7) ^ ((row >> 1) & 7)); ksrc[i] = (row * KW + c * 8) * 2; }
; #pragma unroll
;     for (int i = 0; i < 2; ++i) { const int off = (i * 512 + tid) * 16, sub = off >> 9, rem = (off & 511) >> 1, kk = (sub >> 2) * 8 + (rem >> 5), c = (sub & 3) * 32 + (rem & 31);
;         const int k = (kk & ~0xC) | ((kk & 4) << 1) | ((kk & 8) >> 1); vsrc[i] = (k * VW + c) * 2; }
;     const int vb0 = (int)lds_addr(lds) + v_rd_base(lane);
;     const unsigned ldsw = (unsigned)wid * 1024u;
	v_lshl_add_u32 v187, v7, 4, v4
	v_add_u32_e32 v3, 512, v199
	v_mul_u32_u24_e32 v4, 0xaab, v3
	v_lshrrev_b32_e32 v4, 16, v4
	v_mul_u32_u24_e32 v5, 24, v4
	v_sub_u32_e32 v5, v3, v5
	v_bfe_u32 v6, v4, 1, 3
	v_and_b32_e32 v7, 7, v5
	v_xor_b32_e32 v7, v7, v6
	v_and_or_b32 v7, v5, 24, v7
	v_mul_u32_u24_e32 v4, 0xc00, v4
	v_lshl_add_u32 v188, v7, 4, v4
	v_add_u32_e32 v3, 768, v199
	v_mul_u32_u24_e32 v4, 0xaab, v3
	v_lshrrev_b32_e32 v4, 16, v4
	v_mul_u32_u24_e32 v5, 24, v4
	v_sub_u32_e32 v5, v3, v5
	v_bfe_u32 v6, v4, 1, 3
	v_and_b32_e32 v7, 7, v5
	v_xor_b32_e32 v7, v7, v6
	v_and_or_b32 v7, v5, 24, v7
	v_mul_u32_u24_e32 v4, 0xc00, v4
	v_lshl_add_u32 v189, v7, 4, v4
	v_add_u32_e32 v3, 1024, v199
	v_mul_u32_u24_e32 v4, 0xaab, v3
	v_lshrrev_b32_e32 v4, 16, v4
	v_mul_u32_u24_e32 v5, 24, v4
	v_sub_u32_e32 v5, v3, v5
	v_bfe_u32 v6, v4, 1, 3
	v_and_b32_e32 v7, 7, v5
	v_xor_b32_e32 v7, v7, v6
	v_and_or_b32 v7, v5, 24, v7
	v_mul_u32_u24_e32 v4, 0xc00, v4
	v_lshl_add_u32 v190, v7, 4, v4
	v_add_u32_e32 v3, 1280, v199
	v_mul_u32_u24_e32 v4, 0xaab, v3
	v_lshrrev_b32_e32 v4, 16, v4
	v_mul_u32_u24_e32 v5, 24, v4
	v_sub_u32_e32 v5, v3, v5
	v_bfe_u32 v6, v4, 1, 3
	v_and_b32_e32 v7, 7, v5
	v_xor_b32_e32 v7, v7, v6
	v_and_or_b32 v7, v5, 24, v7
	v_mul_u32_u24_e32 v4, 0xc00, v4
	v_lshl_add_u32 v191, v7, 4, v4
	v_lshrrev_b32_e32 v4, 7, v199
	v_bfe_u32 v5, v199, 2, 3
	v_lshl_or_b32 v4, v4, 3, v5
	v_and_b32_e32 v5, 0xfffffff3, v4
	v_and_b32_e32 v6, 4, v4
	v_lshl_or_b32 v5, v6, 1, v5
	v_and_b32_e32 v6, 8, v4
	v_lshrrev_b32_e32 v6, 1, v6
	v_or_b32_e32 v5, v5, v6
	v_bfe_u32 v6, v199, 5, 2
	v_and_b32_e32 v7, 3, v199
	v_lshlrev_b32_e32 v6, 6, v6
	v_lshl_or_b32 v6, v7, 4, v6
	v_lshl_add_u32 v182, v5, 11, v6
	v_add_u32_e32 v3, 256, v199
	v_lshrrev_b32_e32 v4, 7, v3
	v_bfe_u32 v5, v3, 2, 3
	v_lshl_or_b32 v4, v4, 3, v5
	v_and_b32_e32 v5, 0xfffffff3, v4
	v_and_b32_e32 v6, 4, v4
	v_lshl_or_b32 v5, v6, 1, v5
	v_and_b32_e32 v6, 8, v4
	v_lshrrev_b32_e32 v6, 1, v6
	v_or_b32_e32 v5, v5, v6
	v_bfe_u32 v6, v3, 5, 2
	v_and_b32_e32 v7, 3, v3
	v_lshlrev_b32_e32 v6, 6, v6
	v_lshl_or_b32 v6, v7, 4, v6
	v_lshl_add_u32 v183, v5, 11, v6
	v_add_u32_e32 v3, 512, v199
	v_lshrrev_b32_e32 v4, 7, v3
	v_bfe_u32 v5, v3, 2, 3
	v_lshl_or_b32 v4, v4, 3, v5
	v_and_b32_e32 v5, 0xfffffff3, v4
	v_and_b32_e32 v6, 4, v4
	v_lshl_or_b32 v5, v6, 1, v5
	v_and_b32_e32 v6, 8, v4
	v_lshrrev_b32_e32 v6, 1, v6
	v_or_b32_e32 v5, v5, v6
	v_bfe_u32 v6, v3, 5, 2
	v_and_b32_e32 v7, 3, v3
	v_lshlrev_b32_e32 v6, 6, v6
	v_lshl_or_b32 v6, v7, 4, v6
	v_lshl_add_u32 v184, v5, 11, v6
	v_add_u32_e32 v3, 768, v199
	v_lshrrev_b32_e32 v4, 7, v3
	v_bfe_u32 v5, v3, 2, 3
	v_lshl_or_b32 v4, v4, 3, v5
	v_and_b32_e32 v5, 0xfffffff3, v4
	v_and_b32_e32 v6, 4, v4
	v_lshl_or_b32 v5, v6, 1, v5
	v_and_b32_e32 v6, 8, v4
	v_lshrrev_b32_e32 v6, 1, v6
	v_or_b32_e32 v5, v5, v6
	v_bfe_u32 v6, v3, 5, 2
	v_and_b32_e32 v7, 3, v3
	v_lshlrev_b32_e32 v6, 6, v6
	v_lshl_or_b32 v6, v7, 4, v6
	v_lshl_add_u32 v185, v5, 11, v6
	s_nop 4
	v_and_b32_e32 v4, 31, v199
	v_bfe_u32 v5, v199, 5, 1
	v_bfe_u32 v6, v4, 2, 1
	v_bfe_u32 v7, v4, 3, 1
	v_xor_b32_e32 v6, v6, v7
	v_mul_u32_u24_e32 v7, 12, v6
	v_xor_b32_e32 v8, v4, v7
	v_sub_u32_e32 v9, v8, v4
	v_mul_i32_i24_e32 v9, 0x180, v9
	v_bfe_u32 v6, v4, 1, 3
	v_bfe_u32 v7, v8, 1, 3
	v_or_b32_e32 v10, 0, v5
	v_xor_b32_e32 v11, v10, v7
	v_xor_b32_e32 v12, v10, v6
	v_sub_u32_e32 v11, v11, v12
	v_lshl_add_u32 v11, v11, 4, v9
	v_add_u32_e32 v226, v226, v11
	v_or_b32_e32 v10, 2, v5
	v_xor_b32_e32 v11, v10, v7
	v_xor_b32_e32 v12, v10, v6
	v_sub_u32_e32 v11, v11, v12
	v_lshl_add_u32 v11, v11, 4, v9
	v_add_u32_e32 v227, v227, v11
	v_or_b32_e32 v10, 4, v5
	v_xor_b32_e32 v11, v10, v7
	v_xor_b32_e32 v12, v10, v6
	v_sub_u32_e32 v11, v11, v12
	v_lshl_add_u32 v11, v11, 4, v9
	v_add_u32_e32 v228, v228, v11
	v_or_b32_e32 v10, 6, v5
	v_xor_b32_e32 v11, v10, v7
	v_xor_b32_e32 v12, v10, v6
	v_sub_u32_e32 v11, v11, v12
	v_lshl_add_u32 v11, v11, 4, v9
	v_add_u32_e32 v229, v229, v11

; #define LAS __attribute__((address_space(3)))
; __device__ __forceinline__ unsigned lds_addr(LAS unsigned char* p) { return (unsigned)(size_t)p; }
; #define SBAR() __builtin_amdgcn_sched_barrier(0)
; template <int k> __device__ __forceinline__ void fin_snip(f32x16& p0, f32x16& p1, float alpha, float& l_reg, float& ps, bf16x8& pa0, bf16x8& pa1, bf16x8& pa2, bf16x8& pa3) {
;     if constexpr (k < 8) { p1[2 * k] = __builtin_amdgcn_exp2f(p1[2 * k]); p1[2 * k + 1] = __builtin_amdgcn_exp2f(p1[2 * k + 1]); }
;     else if constexpr (k < 16) { constexpr int j = 2 * (k - 8); const float a = (p0[j] + p0[j + 1]) + (p1[j] + p1[j + 1]); ps = (k == 8) ? a : ps + a; }
;     else if constexpr (k == 16) { auto rr = __builtin_amdgcn_permlane32_swap(__float_as_uint(ps), __float_as_uint(ps), false, false);
;         ps = __uint_as_float(rr[0]) + __uint_as_float(rr[1]); l_reg = l_reg * alpha + ps; }
;     else if constexpr (k == 17) { PK4(p0, 0, pa0); }
;     else if constexpr (k == 18) { PK4(p0, 8, pa1); }
;     else if constexpr (k == 19) { PK4(p1, 0, pa2); }
;     else if constexpr (k == 20) { PK4(p1, 8, pa3); }
; }
; __device__ __forceinline__ void stage_qk_fin(int kboff, f32x16& x0, f32x16& x1, LAS unsigned char* lds, int r32, int hi, const bf16x8* qr,
;                                              f32x16& y0, f32x16& y1, float alY, float& l_reg, bf16x8& pa0, bf16x8& pa1, bf16x8& pa2, bf16x8& pa3) {
;     x0 = (f32x16){}; x1 = (f32x16){};
;     unsigned kb[4];
; #pragma unroll
;     for (int dd = 0; dd < 4; ++dd) kb[dd] = lds_addr(lds) + K_OFF + kboff + r32 * 384 + (((2 * dd + hi) ^ ((r32 >> 1) & 7)) << 4);
;     ...
;     float ps = 0.f; bf16x8 bA[2], bB[2];
;     SBAR(); KGRP(bA, 0); KGRP(bB, 1); KWAIT(bA, 2); SBAR();
;     KMS(bA, 0); KGRP(bA, 2); KWAIT(bB, 2); SBAR();
;     KMS(bB, 1); KGRP(bB, 3); KWAIT(bA, 2); SBAR();
;     KMS(bA, 2); KGRP(bA, 4); KWAIT(bB, 2); SBAR();
;     KMS(bB, 3); KGRP(bB, 5); KWAIT(bA, 2); SBAR();
;     KMS(bA, 4); KGRP(bA, 6); KWAIT(bB, 2); SBAR();
;     KMS(bB, 5); KGRP(bB, 7); KWAIT(bA, 2); SBAR();
;     KMS(bA, 6); KGRP(bA, 8); KWAIT(bB, 2); SBAR();
;     KMS(bB, 7); KGRP(bB, 9); KWAIT(bA, 2); SBAR();
;     KMS(bA, 8); KGRP(bA, 10); KWAIT(bB, 2); SBAR();
;     KMS(bB, 9); KGRP(bB, 11); KWAIT(bA, 2); SBAR();
;     KMS(bA, 10); KWAIT(bB, 0); SBAR();
;     KMS(bB, 11);
.LBB0_328:
	s_cmp_gt_i32 s86, s84
	s_cselect_b64 vcc, -1, 0
	v_cndmask_b32_e32 v216, 0, v223, vcc
	ds_read_b128 v[2:5], v226 offset:0
	ds_read_b128 v[6:9], v226 offset:0x3000
	ds_read_b128 v[10:13], v227 offset:0
	ds_read_b128 v[176:179], v227 offset:0x3000
	s_nop 0
	s_waitcnt lgkmcnt(2)
	s_nop 0
	v_mfma_f32_32x32x16_bf16 v[96:111], v[2:5], v[128:131], 0
	v_exp_f32_e32 v214, v214
	v_exp_f32_e32 v215, v215
	v_mfma_f32_32x32x16_bf16 v[112:127], v[6:9], v[128:131], 0
	v_exp_f32_e32 v212, v212
	v_exp_f32_e32 v213, v213
	ds_read_b128 v[2:5], v228 offset:0
	ds_read_b128 v[6:9], v228 offset:0x3000
	s_waitcnt lgkmcnt(2)
	s_nop 0
	v_mfma_f32_32x32x16_bf16 v[96:111], v[10:13], v[132:135], v[96:111]
	v_exp_f32_e32 v210, v210
	v_exp_f32_e32 v211, v211
	v_mfma_f32_32x32x16_bf16 v[112:127], v[176:179], v[132:135], v[112:127]
	v_exp_f32_e32 v208, v208
	v_exp_f32_e32 v209, v209
	ds_read_b128 v[10:13], v229 offset:0
	ds_read_b128 v[176:179], v229 offset:0x3000
	s_waitcnt lgkmcnt(2)
	s_nop 0
	v_mfma_f32_32x32x16_bf16 v[96:111], v[2:5], v[136:139], v[96:111]
	v_exp_f32_e32 v206, v206
	v_exp_f32_e32 v207, v207
	v_mfma_f32_32x32x16_bf16 v[112:127], v[6:9], v[136:139], v[112:127]
	v_exp_f32_e32 v204, v204
	v_exp_f32_e32 v205, v205
	ds_read_b128 v[2:5], v226 offset:0x80
	ds_read_b128 v[6:9], v226 offset:0x3080
	s_waitcnt lgkmcnt(2)
	s_nop 0
	v_mfma_f32_32x32x16_bf16 v[96:111], v[10:13], v[140:143], v[96:111]
	v_exp_f32_e32 v202, v202
	v_exp_f32_e32 v203, v203
	v_mfma_f32_32x32x16_bf16 v[112:127], v[176:179], v[140:143], v[112:127]
	v_exp_f32_e32 v200, v200
	v_exp_f32_e32 v201, v201
	ds_read_b128 v[10:13], v227 offset:0x80
	ds_read_b128 v[176:179], v227 offset:0x3080
	s_waitcnt lgkmcnt(2)
	s_nop 0
	v_mfma_f32_32x32x16_bf16 v[96:111], v[2:5], v[144:147], v[96:111]
	v_add_f32_e32 v0, v80, v81
	v_add_f32_e32 v2, v214, v215
	v_add_f32_e32 v0, v0, v2
	v_mfma_f32_32x32x16_bf16 v[112:127], v[6:9], v[144:147], v[112:127]
	v_add_f32_e32 v2, v82, v83
	v_add_f32_e32 v3, v212, v213
	v_add_f32_e32 v2, v2, v3
	v_add_f32_e32 v0, v0, v2
	ds_read_b128 v[2:5], v228 offset:0x80
	ds_read_b128 v[6:9], v228 offset:0x3080
	s_waitcnt lgkmcnt(2)
	s_nop 0
	v_mfma_f32_32x32x16_bf16 v[96:111], v[10:13], v[148:151], v[96:111]
	v_add_f32_e32 v10, v84, v85
	v_add_f32_e32 v11, v210, v211
	v_add_f32_e32 v10, v10, v11
	v_add_f32_e32 v0, v10, v0
	v_mfma_f32_32x32x16_bf16 v[112:127], v[176:179], v[148:151], v[112:127]
	v_add_f32_e32 v10, v86, v87
	v_add_f32_e32 v11, v208, v209
	v_add_f32_e32 v10, v10, v11
	v_add_f32_e32 v0, v10, v0
	ds_read_b128 v[10:13], v229 offset:0x80
	ds_read_b128 v[176:179], v229 offset:0x3080
	s_waitcnt lgkmcnt(2)
	s_nop 0
	v_mfma_f32_32x32x16_bf16 v[96:111], v[2:5], v[152:155], v[96:111]
	v_add_f32_e32 v2, v88, v89
	v_add_f32_e32 v3, v206, v207
	v_add_f32_e32 v2, v2, v3
	v_add_f32_e32 v0, v2, v0
	v_mfma_f32_32x32x16_bf16 v[112:127], v[6:9], v[152:155], v[112:127]
	v_add_f32_e32 v2, v90, v91
	v_add_f32_e32 v3, v204, v205
	v_add_f32_e32 v2, v2, v3
	v_add_f32_e32 v0, v2, v0
	ds_read_b128 v[2:5], v226 offset:0x100
	ds_read_b128 v[6:9], v226 offset:0x3100
	s_waitcnt lgkmcnt(2)
	s_nop 0
	v_mfma_f32_32x32x16_bf16 v[96:111], v[10:13], v[156:159], v[96:111]
	v_add_f32_e32 v10, v92, v93
	v_add_f32_e32 v11, v202, v203
	v_add_f32_e32 v10, v10, v11
	v_add_f32_e32 v0, v10, v0
	v_mfma_f32_32x32x16_bf16 v[112:127], v[176:179], v[156:159], v[112:127]
	v_add_f32_e32 v10, v94, v95
	v_add_f32_e32 v11, v200, v201
	v_add_f32_e32 v10, v10, v11
	v_add_f32_e32 v14, v10, v0
	ds_read_b128 v[10:13], v227 offset:0x100
	ds_read_b128 v[176:179], v227 offset:0x3100
	s_waitcnt lgkmcnt(2)
	s_nop 0
	v_mfma_f32_32x32x16_bf16 v[96:111], v[2:5], v[160:163], v[96:111]
	v_mov_b32_e32 v15, v14
	s_nop 1
	v_permlane32_swap_b32_e32 v14, v15
	v_mfma_f32_32x32x16_bf16 v[112:127], v[6:9], v[160:163], v[112:127]
	v_cvt_pk_bf16_f32 v2, v80, v81
	v_cvt_pk_bf16_f32 v3, v82, v83
	v_cvt_pk_bf16_f32 v4, v84, v85
	v_cvt_pk_bf16_f32 v5, v86, v87
	ds_read_b128 v[194:197], v228 offset:0x100
	ds_read_b128 v[232:235], v228 offset:0x3100
	s_waitcnt lgkmcnt(2)
	s_nop 0
	v_mfma_f32_32x32x16_bf16 v[96:111], v[10:13], v[164:167], v[96:111]
	v_cvt_pk_bf16_f32 v6, v88, v89
	v_cvt_pk_bf16_f32 v7, v90, v91
	v_cvt_pk_bf16_f32 v8, v92, v93
	v_cvt_pk_bf16_f32 v9, v94, v95
	v_mfma_f32_32x32x16_bf16 v[112:127], v[176:179], v[164:167], v[112:127]
	v_cvt_pk_bf16_f32 v10, v214, v215
	v_cvt_pk_bf16_f32 v11, v212, v213
	v_cvt_pk_bf16_f32 v12, v210, v211
	v_cvt_pk_bf16_f32 v13, v208, v209
	ds_read_b128 v[236:239], v229 offset:0x100
	ds_read_b128 v[240:243], v229 offset:0x3100
	s_waitcnt lgkmcnt(2)
	s_nop 0
	v_mfma_f32_32x32x16_bf16 v[96:111], v[194:197], v[168:171], v[96:111]
	v_cvt_pk_bf16_f32 v176, v206, v207
	v_cvt_pk_bf16_f32 v177, v204, v205
	v_cvt_pk_bf16_f32 v178, v202, v203
	v_cvt_pk_bf16_f32 v179, v200, v201
	v_mfma_f32_32x32x16_bf16 v[112:127], v[232:235], v[168:171], v[112:127]
	v_add_f32_e32 v245, v14, v15
	v_fmac_f32_e32 v245, v192, v230
	s_waitcnt lgkmcnt(0)
	s_nop 0
	v_mfma_f32_32x32x16_bf16 v[96:111], v[236:239], v[172:175], v[96:111]
	v_mfma_f32_32x32x16_bf16 v[112:127], v[240:243], v[172:175], v[112:127]
	s_cmp_eq_u32 s100, 0
	s_cbranch_scc1 .Lmy_mid_a
	s_waitcnt vmcnt(0)
	s_barrier

; #define LAS __attribute__((address_space(3)))
; __device__ __forceinline__ unsigned lds_addr(LAS unsigned char* p) { return (unsigned)(size_t)p; }
; #define SBAR() __builtin_amdgcn_sched_barrier(0)
; template <int k> __device__ __forceinline__ void fin_snip(f32x16& p0, f32x16& p1, float alpha, float& l_reg, float& ps, bf16x8& pa0, bf16x8& pa1, bf16x8& pa2, bf16x8& pa3) {
;     if constexpr (k < 8) { p1[2 * k] = __builtin_amdgcn_exp2f(p1[2 * k]); p1[2 * k + 1] = __builtin_amdgcn_exp2f(p1[2 * k + 1]); }
;     else if constexpr (k < 16) { constexpr int j = 2 * (k - 8); const float a = (p0[j] + p0[j + 1]) + (p1[j] + p1[j + 1]); ps = (k == 8) ? a : ps + a; }
;     else if constexpr (k == 16) { auto rr = __builtin_amdgcn_permlane32_swap(__float_as_uint(ps), __float_as_uint(ps), false, false);
;         ps = __uint_as_float(rr[0]) + __uint_as_float(rr[1]); l_reg = l_reg * alpha + ps; }
;     else if constexpr (k == 17) { PK4(p0, 0, pa0); }
;     else if constexpr (k == 18) { PK4(p0, 8, pa1); }
;     else if constexpr (k == 19) { PK4(p1, 0, pa2); }
;     else if constexpr (k == 20) { PK4(p1, 8, pa3); }
; }
; __device__ __forceinline__ void stage_qk_fin(int kboff, f32x16& x0, f32x16& x1, LAS unsigned char* lds, int r32, int hi, const bf16x8* qr,
;                                              f32x16& y0, f32x16& y1, float alY, float& l_reg, bf16x8& pa0, bf16x8& pa1, bf16x8& pa2, bf16x8& pa3) {
;     x0 = (f32x16){}; x1 = (f32x16){};
;     unsigned kb[4];
; #pragma unroll
;     for (int dd = 0; dd < 4; ++dd) kb[dd] = lds_addr(lds) + K_OFF + kboff + r32 * 384 + (((2 * dd + hi) ^ ((r32 >> 1) & 7)) << 4);
;     ...
;     float ps = 0.f; bf16x8 bA[2], bB[2];
;     SBAR(); KGRP(bA, 0); KGRP(bB, 1); KWAIT(bA, 2); SBAR();
;     KMS(bA, 0); KGRP(bA, 2); KWAIT(bB, 2); SBAR();
;     KMS(bB, 1); KGRP(bB, 3); KWAIT(bA, 2); SBAR();
;     KMS(bA, 2); KGRP(bA, 4); KWAIT(bB, 2); SBAR();
;     KMS(bB, 3); KGRP(bB, 5); KWAIT(bA, 2); SBAR();
;     KMS(bA, 4); KGRP(bA, 6); KWAIT(bB, 2); SBAR();
;     KMS(bB, 5); KGRP(bB, 7); KWAIT(bA, 2); SBAR();
;     KMS(bA, 6); KGRP(bA, 8); KWAIT(bB, 2); SBAR();
;     KMS(bB, 7); KGRP(bB, 9); KWAIT(bA, 2); SBAR();
;     KMS(bA, 8); KGRP(bA, 10); KWAIT(bB, 2); SBAR();
;     KMS(bB, 9); KGRP(bB, 11); KWAIT(bA, 2); SBAR();
;     KMS(bA, 10); KWAIT(bB, 0); SBAR();
;     KMS(bB, 11);
.LBB0_333:
	s_add_i32 s34, s85, 0xffff4000
	s_cmp_lt_i32 s86, s84
	s_cselect_b64 s[86:87], -1, 0
	v_cndmask_b32_e64 v178, v223, 0, s[86:87]
	ds_read_b128 v[2:5], v181 offset:0
	ds_read_b128 v[6:9], v181 offset:0x3000
	ds_read_b128 v[10:13], v219 offset:0
	ds_read_b128 v[112:115], v219 offset:0x3000
	s_nop 0
	s_waitcnt lgkmcnt(2)
	s_nop 0
	v_mfma_f32_32x32x16_bf16 v[96:111], v[2:5], v[128:131], 0
	v_exp_f32_e32 v14, v14
	v_exp_f32_e32 v15, v15
	v_mfma_f32_32x32x16_bf16 v[80:95], v[6:9], v[128:131], 0
	v_exp_f32_e32 v176, v176
	v_exp_f32_e32 v177, v177
	ds_read_b128 v[2:5], v220 offset:0
	ds_read_b128 v[6:9], v220 offset:0x3000
	s_waitcnt lgkmcnt(2)
	s_nop 0
	v_mfma_f32_32x32x16_bf16 v[96:111], v[10:13], v[132:135], v[96:111]
	v_exp_f32_e32 v116, v116
	v_exp_f32_e32 v117, v117
	v_mfma_f32_32x32x16_bf16 v[80:95], v[112:115], v[132:135], v[80:95]
	v_exp_f32_e32 v118, v118
	v_exp_f32_e32 v119, v119
	ds_read_b128 v[10:13], v221 offset:0
	ds_read_b128 v[112:115], v221 offset:0x3000
	s_waitcnt lgkmcnt(2)
	s_nop 0
	v_mfma_f32_32x32x16_bf16 v[96:111], v[2:5], v[136:139], v[96:111]
	v_exp_f32_e32 v120, v120
	v_exp_f32_e32 v121, v121
	v_mfma_f32_32x32x16_bf16 v[80:95], v[6:9], v[136:139], v[80:95]
	v_exp_f32_e32 v122, v122
	v_exp_f32_e32 v123, v123
	ds_read_b128 v[2:5], v181 offset:0x80
	ds_read_b128 v[6:9], v181 offset:0x3080
	s_waitcnt lgkmcnt(2)
	s_nop 0
	v_mfma_f32_32x32x16_bf16 v[96:111], v[10:13], v[140:143], v[96:111]
	v_exp_f32_e32 v124, v124
	v_exp_f32_e32 v125, v125
	v_mfma_f32_32x32x16_bf16 v[80:95], v[112:115], v[140:143], v[80:95]
	v_exp_f32_e32 v126, v126
	v_exp_f32_e32 v127, v127
	ds_read_b128 v[10:13], v219 offset:0x80
	ds_read_b128 v[112:115], v219 offset:0x3080
	s_waitcnt lgkmcnt(2)
	s_nop 0
	v_mfma_f32_32x32x16_bf16 v[96:111], v[2:5], v[144:147], v[96:111]
	v_add_f32_e32 v2, v243, v242
	v_add_f32_e32 v3, v14, v15
	v_add_f32_e32 v2, v2, v3
	v_mfma_f32_32x32x16_bf16 v[80:95], v[6:9], v[144:147], v[80:95]
	v_add_f32_e32 v3, v241, v240
	v_add_f32_e32 v4, v176, v177
	v_add_f32_e32 v3, v3, v4
	v_add_f32_e32 v192, v2, v3
	ds_read_b128 v[2:5], v220 offset:0x80
	ds_read_b128 v[6:9], v220 offset:0x3080
	s_waitcnt lgkmcnt(2)
	s_nop 0
	v_mfma_f32_32x32x16_bf16 v[96:111], v[10:13], v[148:151], v[96:111]
	v_add_f32_e32 v10, v239, v238
	v_add_f32_e32 v11, v116, v117
	v_add_f32_e32 v10, v10, v11
	v_add_f32_e32 v10, v10, v192
	v_mfma_f32_32x32x16_bf16 v[80:95], v[112:115], v[148:151], v[80:95]
	v_add_f32_e32 v11, v237, v236
	v_add_f32_e32 v12, v118, v119
	v_add_f32_e32 v11, v11, v12
	v_add_f32_e32 v192, v11, v10
	ds_read_b128 v[10:13], v221 offset:0x80
	ds_read_b128 v[112:115], v221 offset:0x3080
	s_waitcnt lgkmcnt(2)
	s_nop 0
	v_mfma_f32_32x32x16_bf16 v[96:111], v[2:5], v[152:155], v[96:111]
	v_add_f32_e32 v2, v235, v234
	v_add_f32_e32 v3, v120, v121
	v_add_f32_e32 v2, v2, v3
	v_add_f32_e32 v2, v2, v192
	v_mfma_f32_32x32x16_bf16 v[80:95], v[6:9], v[152:155], v[80:95]
	v_add_f32_e32 v3, v233, v232
	v_add_f32_e32 v4, v122, v123
	v_add_f32_e32 v3, v3, v4
	v_add_f32_e32 v192, v3, v2
	ds_read_b128 v[2:5], v181 offset:0x100
	ds_read_b128 v[6:9], v181 offset:0x3100
	s_waitcnt lgkmcnt(2)
	s_nop 0
	v_mfma_f32_32x32x16_bf16 v[96:111], v[10:13], v[156:159], v[96:111]
	v_add_f32_e32 v10, v231, v230
	v_add_f32_e32 v11, v124, v125
	v_add_f32_e32 v10, v10, v11
	v_add_f32_e32 v10, v10, v192
	v_mfma_f32_32x32x16_bf16 v[80:95], v[112:115], v[156:159], v[80:95]
	v_add_f32_e32 v11, v216, v179
	v_add_f32_e32 v12, v126, v127
	v_add_f32_e32 v11, v11, v12
	v_add_f32_e32 v200, v11, v10
	ds_read_b128 v[10:13], v219 offset:0x100
	ds_read_b128 v[112:115], v219 offset:0x3100
	s_waitcnt lgkmcnt(2)
	s_nop 0
	v_mfma_f32_32x32x16_bf16 v[96:111], v[2:5], v[160:163], v[96:111]
	v_mov_b32_e32 v201, v200
	s_nop 1
	v_permlane32_swap_b32_e32 v200, v201
	v_mfma_f32_32x32x16_bf16 v[80:95], v[6:9], v[160:163], v[80:95]
	v_cvt_pk_bf16_f32 v2, v243, v242
	v_cvt_pk_bf16_f32 v3, v241, v240
	v_cvt_pk_bf16_f32 v4, v239, v238
	v_cvt_pk_bf16_f32 v5, v237, v236
	ds_read_b128 v[194:197], v220 offset:0x100
	ds_read_b128 v[202:205], v220 offset:0x3100
	s_waitcnt lgkmcnt(2)
	s_nop 0
	v_mfma_f32_32x32x16_bf16 v[96:111], v[10:13], v[164:167], v[96:111]
	v_cvt_pk_bf16_f32 v6, v235, v234
	v_cvt_pk_bf16_f32 v7, v233, v232
	v_cvt_pk_bf16_f32 v8, v231, v230
	v_cvt_pk_bf16_f32 v9, v216, v179
	v_mfma_f32_32x32x16_bf16 v[80:95], v[112:115], v[164:167], v[80:95]
	v_cvt_pk_bf16_f32 v10, v14, v15
	v_cvt_pk_bf16_f32 v11, v176, v177
	v_cvt_pk_bf16_f32 v12, v116, v117
	v_cvt_pk_bf16_f32 v13, v118, v119
	ds_read_b128 v[206:209], v221 offset:0x100
	ds_read_b128 v[210:213], v221 offset:0x3100
	s_waitcnt lgkmcnt(2)
	s_nop 0
	v_mfma_f32_32x32x16_bf16 v[96:111], v[194:197], v[168:171], v[96:111]
	v_cvt_pk_bf16_f32 v112, v120, v121
	v_cvt_pk_bf16_f32 v113, v122, v123
	v_cvt_pk_bf16_f32 v114, v124, v125
	v_cvt_pk_bf16_f32 v115, v126, v127
	v_mfma_f32_32x32x16_bf16 v[80:95], v[202:205], v[168:171], v[80:95]
	v_add_f32_e32 v247, v200, v201
	v_fmac_f32_e32 v247, v245, v0
	v_mov_b32_e32 v245, v247
	s_waitcnt lgkmcnt(0)
	s_nop 0
	v_mfma_f32_32x32x16_bf16 v[96:111], v[206:209], v[172:175], v[96:111]
	v_mfma_f32_32x32x16_bf16 v[80:95], v[210:213], v[172:175], v[80:95]
	s_cmp_eq_u32 s100, 0
	s_cbranch_scc1 .Lmy_mid_b
	s_waitcnt vmcnt(0)
	s_barrier
